# v24 + K-loop LDS-DMA issue balanced 4/4/4/4 per phase (A stages in odd phases, B in even; waits 8/6/8/6; next unit's A(k1,half0) staged once behind the loop)
# speedup vs baseline: 1.0290x; 1.0149x over previous
; #define PG8_WAIT_V(n) asm volatile("s_waitcnt vmcnt(" #n ")" ::: "memory")
; template <class Epi, bool ALIGN_EPI, bool SP2, class Hook>
; __device__ __forceinline__ void gemm_phase(LAS unsigned char* lds, const Gemm g, const StaticOrder& S, const Epi& E, Acc& acc, const bool fresh, const Hook& H, const int wave_id) {
;     ...
;         if constexpr (SP2 && Epi::NSTORE > 0) {
;             const Src a1 = cA + kstep, a2 = cA + 2 * kstep, b2 = cB + 2 * kstep, a3 = a2 + kstep, b3 = b2 + kstep;
;             if constexpr (Epi::NSTORE == 16) PG8_TRIP_SP2(PG8_WAIT_V(24)); else PG8_TRIP_SP2(PG8_WAIT_V(16));
;             t0 = 2;
.LBB0_382:
	ds_read_b128 v[2:5], v150
	ds_read_b128 v[6:9], v150 offset:1024
	ds_read_b128 v[10:13], v150 offset:2048
	ds_read_b128 v[14:17], v150 offset:3072
	ds_read_b128 v[18:21], v151
	ds_read_b128 v[22:25], v151 offset:1024
	ds_read_b128 v[26:29], v151 offset:2048
	ds_read_b128 v[30:33], v151 offset:3072
	s_or_b32 s9, s68, 0x100
	s_or_b32 s8, s68, 0x180
	s_or_b32 s10, s69, 0x100
	s_or_b32 s11, s68, 0x40080
	s_mov_b32 m0, s45
	ds_read_b128 v[34:37], v149
	ds_read_b128 v[38:41], v149 offset:1024
	ds_read_b128 v[42:45], v149 offset:2048
	ds_read_b128 v[46:49], v149 offset:3072
	ds_read_b128 v[50:53], v149 offset:4096
	ds_read_b128 v[54:57], v149 offset:5120
	ds_read_b128 v[58:61], v149 offset:6144
	ds_read_b128 v[62:65], v149 offset:7168
	buffer_load_dwordx4 v144, s[0:3], s11 offen lds
	s_mov_b32 m0, s46
	s_nop 0
	buffer_load_dwordx4 v146, s[0:3], s11 offen lds
	s_waitcnt vmcnt(24)
	s_waitcnt lgkmcnt(0)
	s_setprio 1
	s_barrier
	v_mfma_f32_16x16x32_bf16 v[86:89], v[10:13], v[50:53], 0
	v_mfma_f32_16x16x32_bf16 v[92:95], v[14:17], v[54:57], v[86:89]
	v_mfma_f32_16x16x32_bf16 v[86:89], v[2:5], v[58:61], 0
	v_mfma_f32_16x16x32_bf16 v[66:69], v[2:5], v[34:37], 0
	v_mfma_f32_16x16x32_bf16 v[70:73], v[10:13], v[34:37], 0
	v_mfma_f32_16x16x32_bf16 v[74:77], v[2:5], v[42:45], 0
	v_mfma_f32_16x16x32_bf16 v[78:81], v[10:13], v[42:45], 0
	v_mfma_f32_16x16x32_bf16 v[82:85], v[2:5], v[50:53], 0
	v_mfma_f32_16x16x32_bf16 v[96:99], v[6:9], v[62:65], v[86:89]
	v_mfma_f32_16x16x32_bf16 v[86:89], v[10:13], v[58:61], 0
	v_mfma_f32_16x16x32_bf16 v[66:69], v[6:9], v[38:41], v[66:69]
	v_mfma_f32_16x16x32_bf16 v[70:73], v[14:17], v[38:41], v[70:73]
	v_mfma_f32_16x16x32_bf16 v[74:77], v[6:9], v[46:49], v[74:77]
	v_mfma_f32_16x16x32_bf16 v[78:81], v[14:17], v[46:49], v[78:81]
	v_mfma_f32_16x16x32_bf16 v[82:85], v[6:9], v[54:57], v[82:85]
	v_mfma_f32_16x16x32_bf16 v[104:107], v[14:17], v[62:65], v[86:89]
	v_mfma_f32_16x16x32_bf16 v[86:89], v[18:21], v[34:37], 0
	v_mfma_f32_16x16x32_bf16 v[34:37], v[26:29], v[34:37], 0
	v_mfma_f32_16x16x32_bf16 v[116:119], v[30:33], v[38:41], v[34:37]
	v_mfma_f32_16x16x32_bf16 v[34:37], v[18:21], v[42:45], 0
	v_mfma_f32_16x16x32_bf16 v[132:135], v[22:25], v[46:49], v[34:37]
	v_mfma_f32_16x16x32_bf16 v[34:37], v[26:29], v[42:45], 0
	v_mfma_f32_16x16x32_bf16 v[108:111], v[22:25], v[38:41], v[86:89]
	v_mfma_f32_16x16x32_bf16 v[40:43], v[30:33], v[46:49], v[34:37]
	v_mfma_f32_16x16x32_bf16 v[34:37], v[18:21], v[50:53], 0
	v_mfma_f32_16x16x32_bf16 v[44:47], v[22:25], v[54:57], v[34:37]
	v_mfma_f32_16x16x32_bf16 v[34:37], v[26:29], v[50:53], 0
	v_mfma_f32_16x16x32_bf16 v[48:51], v[30:33], v[54:57], v[34:37]
	v_mfma_f32_16x16x32_bf16 v[34:37], v[18:21], v[58:61], 0
	v_mfma_f32_16x16x32_bf16 v[52:55], v[22:25], v[62:65], v[34:37]
	v_mfma_f32_16x16x32_bf16 v[34:37], v[26:29], v[58:61], 0
	v_mfma_f32_16x16x32_bf16 v[60:63], v[30:33], v[62:65], v[34:37]
	s_barrier
	s_setprio 0
	s_mov_b32 m0, s92
	s_nop 3
	ds_read_b128 v[34:37], v149 offset:16384
	ds_read_b128 v[56:59], v149 offset:17408
	ds_read_b128 v[86:89], v149 offset:18432
	ds_read_b128 v[100:103], v149 offset:19456
	ds_read_b128 v[112:115], v149 offset:20480
	ds_read_b128 v[120:123], v149 offset:21504
	ds_read_b128 v[124:127], v149 offset:22528
	ds_read_b128 v[128:131], v149 offset:23552
	buffer_load_dwordx4 v145, s[4:7], s10 offen lds
	s_mov_b32 m0, s93
	s_nop 0
	buffer_load_dwordx4 v147, s[4:7], s10 offen lds
	s_or_b32 s10, s69, 0x40100
	s_mov_b32 m0, s94
	s_nop 0
	buffer_load_dwordx4 v145, s[4:7], s10 offen lds
	s_mov_b32 m0, s95
	s_nop 0
	buffer_load_dwordx4 v147, s[4:7], s10 offen lds
	s_waitcnt vmcnt(22)
	s_waitcnt lgkmcnt(0)
	s_setprio 1
	s_barrier
	v_mfma_f32_16x16x32_bf16 v[136:139], v[2:5], v[34:37], 0
	v_mfma_f32_16x16x32_bf16 v[154:157], v[2:5], v[86:89], 0
	v_mfma_f32_16x16x32_bf16 v[162:165], v[2:5], v[112:115], 0
	v_mfma_f32_16x16x32_bf16 v[2:5], v[2:5], v[124:127], 0
	v_mfma_f32_16x16x32_bf16 v[136:139], v[6:9], v[56:59], v[136:139]
	v_mfma_f32_16x16x32_bf16 v[140:143], v[10:13], v[34:37], 0
	v_mfma_f32_16x16x32_bf16 v[154:157], v[6:9], v[100:103], v[154:157]
	v_mfma_f32_16x16x32_bf16 v[158:161], v[10:13], v[86:89], 0
	v_mfma_f32_16x16x32_bf16 v[162:165], v[6:9], v[120:123], v[162:165]
	v_mfma_f32_16x16x32_bf16 v[166:169], v[10:13], v[112:115], 0
	v_mfma_f32_16x16x32_bf16 v[2:5], v[6:9], v[128:131], v[2:5]
	v_mfma_f32_16x16x32_bf16 v[6:9], v[10:13], v[124:127], 0
	v_mfma_f32_16x16x32_bf16 v[140:143], v[14:17], v[56:59], v[140:143]
	v_mfma_f32_16x16x32_bf16 v[158:161], v[14:17], v[100:103], v[158:161]
	v_mfma_f32_16x16x32_bf16 v[166:169], v[14:17], v[120:123], v[166:169]
	v_mfma_f32_16x16x32_bf16 v[170:173], v[14:17], v[128:131], v[6:9]
	v_mfma_f32_16x16x32_bf16 v[6:9], v[18:21], v[34:37], 0
	v_mfma_f32_16x16x32_bf16 v[174:177], v[22:25], v[56:59], v[6:9]
	v_mfma_f32_16x16x32_bf16 v[6:9], v[26:29], v[34:37], 0
	v_mfma_f32_16x16x32_bf16 v[178:181], v[30:33], v[56:59], v[6:9]
	v_mfma_f32_16x16x32_bf16 v[6:9], v[18:21], v[86:89], 0
	v_mfma_f32_16x16x32_bf16 v[182:185], v[22:25], v[100:103], v[6:9]
	v_mfma_f32_16x16x32_bf16 v[6:9], v[26:29], v[86:89], 0
	v_mfma_f32_16x16x32_bf16 v[186:189], v[30:33], v[100:103], v[6:9]
	v_mfma_f32_16x16x32_bf16 v[6:9], v[18:21], v[112:115], 0
	v_mfma_f32_16x16x32_bf16 v[190:193], v[22:25], v[120:123], v[6:9]
	v_mfma_f32_16x16x32_bf16 v[6:9], v[26:29], v[112:115], 0
	v_mfma_f32_16x16x32_bf16 v[212:215], v[30:33], v[120:123], v[6:9]
	v_mfma_f32_16x16x32_bf16 v[6:9], v[18:21], v[124:127], 0
	v_mfma_f32_16x16x32_bf16 v[20:23], v[22:25], v[128:131], v[6:9]
	v_mfma_f32_16x16x32_bf16 v[6:9], v[26:29], v[124:127], 0
	v_mfma_f32_16x16x32_bf16 v[216:219], v[30:33], v[128:131], v[6:9]
	s_barrier
; #define PG8_WAIT_V(n) asm volatile("s_waitcnt vmcnt(" #n ")" ::: "memory")
; template <class Epi, bool ALIGN_EPI, bool SP2, class Hook>
; __device__ __forceinline__ void gemm_phase(LAS unsigned char* lds, const Gemm g, const StaticOrder& S, const Epi& E, Acc& acc, const bool fresh, const Hook& H, const int wave_id) {
;     ...
;         if constexpr (SP2 && Epi::NSTORE > 0) {
;             const Src a1 = cA + kstep, a2 = cA + 2 * kstep, b2 = cB + 2 * kstep, a3 = a2 + kstep, b3 = b2 + kstep;
;             if constexpr (Epi::NSTORE == 16) PG8_TRIP_SP2(PG8_WAIT_V(24)); else PG8_TRIP_SP2(PG8_WAIT_V(16));
;             t0 = 2;
	s_setprio 0
	s_mov_b32 m0, s44
	s_nop 0
	buffer_load_dwordx4 v144, s[0:3], s9 offen lds
	s_mov_b32 m0, s36
	s_nop 0
	buffer_load_dwordx4 v146, s[0:3], s9 offen lds
	s_nop 4
	ds_read_b128 v[6:9], v152
	ds_read_b128 v[24:27], v152 offset:1024
	ds_read_b128 v[228:231], v152 offset:2048
	ds_read_b128 v[232:235], v152 offset:3072
	ds_read_b128 v[236:239], v153
	ds_read_b128 v[240:243], v153 offset:1024
	ds_read_b128 v[244:247], v153 offset:2048
	ds_read_b128 v[150:153], v153 offset:3072
	s_or_b32 s9, s68, 0x40100
	s_mov_b32 m0, s37
	ds_read_b128 v[10:13], v149 offset:32768
	ds_read_b128 v[14:17], v149 offset:33792
	ds_read_b128 v[32:35], v149 offset:34816
	ds_read_b128 v[194:197], v149 offset:35840
	ds_read_b128 v[208:211], v149 offset:36864
	ds_read_b128 v[200:203], v149 offset:37888
	ds_read_b128 v[204:207], v149 offset:38912
	ds_read_b128 v[220:223], v149 offset:39936
	buffer_load_dwordx4 v144, s[0:3], s9 offen lds
	s_mov_b32 m0, s38
	s_nop 0
	buffer_load_dwordx4 v146, s[0:3], s9 offen lds
	s_waitcnt vmcnt(8)
	s_waitcnt lgkmcnt(0)
	s_setprio 1
	s_barrier
	v_mfma_f32_16x16x32_bf16 v[28:31], v[6:9], v[10:13], v[66:69]
	v_mfma_f32_16x16x32_bf16 v[120:123], v[24:27], v[14:17], v[28:31]
	v_mfma_f32_16x16x32_bf16 v[28:31], v[228:231], v[10:13], v[70:73]
	v_mfma_f32_16x16x32_bf16 v[112:115], v[232:235], v[14:17], v[28:31]
	v_mfma_f32_16x16x32_bf16 v[28:31], v[6:9], v[32:35], v[74:77]
	v_mfma_f32_16x16x32_bf16 v[100:103], v[24:27], v[194:197], v[28:31]
	v_mfma_f32_16x16x32_bf16 v[28:31], v[228:231], v[32:35], v[78:81]
	v_mfma_f32_16x16x32_bf16 v[88:91], v[232:235], v[194:197], v[28:31]
	v_mfma_f32_16x16x32_bf16 v[28:31], v[6:9], v[208:211], v[82:85]
	v_mfma_f32_16x16x32_bf16 v[68:71], v[24:27], v[200:203], v[28:31]
	v_mfma_f32_16x16x32_bf16 v[28:31], v[228:231], v[208:211], v[92:95]
	v_mfma_f32_16x16x32_bf16 v[56:59], v[232:235], v[200:203], v[28:31]
	v_mfma_f32_16x16x32_bf16 v[28:31], v[6:9], v[204:207], v[96:99]
	v_mfma_f32_16x16x32_bf16 v[36:39], v[24:27], v[220:223], v[28:31]
	v_mfma_f32_16x16x32_bf16 v[28:31], v[228:231], v[204:207], v[104:107]
	v_mfma_f32_16x16x32_bf16 v[28:31], v[232:235], v[220:223], v[28:31]
	v_mfma_f32_16x16x32_bf16 v[64:67], v[236:239], v[10:13], v[108:111]
	v_mfma_f32_16x16x32_bf16 v[10:13], v[244:247], v[10:13], v[116:119]
	v_mfma_f32_16x16x32_bf16 v[124:127], v[150:153], v[14:17], v[10:13]
	v_mfma_f32_16x16x32_bf16 v[10:13], v[236:239], v[32:35], v[132:135]
	v_mfma_f32_16x16x32_bf16 v[116:119], v[240:243], v[194:197], v[10:13]
	v_mfma_f32_16x16x32_bf16 v[10:13], v[244:247], v[32:35], v[40:43]
	v_mfma_f32_16x16x32_bf16 v[108:111], v[150:153], v[194:197], v[10:13]
	v_mfma_f32_16x16x32_bf16 v[10:13], v[236:239], v[208:211], v[44:47]
	v_mfma_f32_16x16x32_bf16 v[92:95], v[240:243], v[200:203], v[10:13]
	v_mfma_f32_16x16x32_bf16 v[10:13], v[244:247], v[208:211], v[48:51]
	v_mfma_f32_16x16x32_bf16 v[80:83], v[150:153], v[200:203], v[10:13]
	v_mfma_f32_16x16x32_bf16 v[10:13], v[236:239], v[204:207], v[52:55]
	v_mfma_f32_16x16x32_bf16 v[128:131], v[240:243], v[14:17], v[64:67]
	v_mfma_f32_16x16x32_bf16 v[64:67], v[240:243], v[220:223], v[10:13]
	v_mfma_f32_16x16x32_bf16 v[10:13], v[244:247], v[204:207], v[60:63]
	v_mfma_f32_16x16x32_bf16 v[48:51], v[150:153], v[220:223], v[10:13]
	s_barrier
	s_setprio 0
	s_mov_b32 m0, s39
	s_or_b32 s9, s69, 0x180
	ds_read_b128 v[44:47], v149 offset:49152
	ds_read_b128 v[52:55], v149 offset:50176
	ds_read_b128 v[76:79], v149 offset:51200
	ds_read_b128 v[132:135], v149 offset:52224
	ds_read_b128 v[194:197], v149 offset:53248
	ds_read_b128 v[200:203], v149 offset:54272
	ds_read_b128 v[204:207], v149 offset:55296
	ds_read_b128 v[208:211], v149 offset:56320
	buffer_load_dwordx4 v145, s[4:7], s9 offen lds
	s_mov_b32 m0, s40
	s_nop 0
	buffer_load_dwordx4 v147, s[4:7], s9 offen lds
	s_or_b32 s9, s69, 0x40180
	s_mov_b32 m0, s43
	s_nop 0
	buffer_load_dwordx4 v145, s[4:7], s9 offen lds
	s_mov_b32 m0, s42
	s_nop 0
	buffer_load_dwordx4 v147, s[4:7], s9 offen lds
	s_waitcnt vmcnt(6)
	s_waitcnt lgkmcnt(0)
	s_setprio 1
	s_barrier
	v_mfma_f32_16x16x32_bf16 v[10:13], v[6:9], v[44:47], v[136:139]
	v_mfma_f32_16x16x32_bf16 v[72:75], v[24:27], v[52:55], v[10:13]
	v_mfma_f32_16x16x32_bf16 v[10:13], v[228:231], v[44:47], v[140:143]
	v_mfma_f32_16x16x32_bf16 v[60:63], v[232:235], v[52:55], v[10:13]
	v_mfma_f32_16x16x32_bf16 v[10:13], v[6:9], v[76:79], v[154:157]
	v_mfma_f32_16x16x32_bf16 v[40:43], v[24:27], v[132:135], v[10:13]
	v_mfma_f32_16x16x32_bf16 v[10:13], v[228:231], v[76:79], v[158:161]
	v_mfma_f32_16x16x32_bf16 v[32:35], v[232:235], v[132:135], v[10:13]
	v_mfma_f32_16x16x32_bf16 v[10:13], v[6:9], v[194:197], v[162:165]
	v_mfma_f32_16x16x32_bf16 v[16:19], v[24:27], v[200:203], v[10:13]
	v_mfma_f32_16x16x32_bf16 v[10:13], v[228:231], v[194:197], v[166:169]
	v_mfma_f32_16x16x32_bf16 v[2:5], v[6:9], v[204:207], v[2:5]
	v_mfma_f32_16x16x32_bf16 v[12:15], v[232:235], v[200:203], v[10:13]
	v_mfma_f32_16x16x32_bf16 v[8:11], v[24:27], v[208:211], v[2:5]
	v_mfma_f32_16x16x32_bf16 v[2:5], v[228:231], v[204:207], v[170:173]
	v_mfma_f32_16x16x32_bf16 v[4:7], v[232:235], v[208:211], v[2:5]
	v_mfma_f32_16x16x32_bf16 v[24:27], v[236:239], v[44:47], v[174:177]
	v_mfma_f32_16x16x32_bf16 v[96:99], v[240:243], v[52:55], v[24:27]
	v_mfma_f32_16x16x32_bf16 v[24:27], v[244:247], v[44:47], v[178:181]
	v_mfma_f32_16x16x32_bf16 v[104:107], v[150:153], v[52:55], v[24:27]
	v_mfma_f32_16x16x32_bf16 v[24:27], v[236:239], v[76:79], v[182:185]
	v_mfma_f32_16x16x32_bf16 v[84:87], v[240:243], v[132:135], v[24:27]
	v_mfma_f32_16x16x32_bf16 v[24:27], v[244:247], v[76:79], v[186:189]
	v_mfma_f32_16x16x32_bf16 v[76:79], v[150:153], v[132:135], v[24:27]
	v_mfma_f32_16x16x32_bf16 v[24:27], v[236:239], v[194:197], v[190:193]
	v_mfma_f32_16x16x32_bf16 v[52:55], v[240:243], v[200:203], v[24:27]
	v_mfma_f32_16x16x32_bf16 v[24:27], v[244:247], v[194:197], v[212:215]
	v_mfma_f32_16x16x32_bf16 v[20:23], v[236:239], v[204:207], v[20:23]
	v_mfma_f32_16x16x32_bf16 v[44:47], v[150:153], v[200:203], v[24:27]
	v_mfma_f32_16x16x32_bf16 v[24:27], v[240:243], v[208:211], v[20:23]
	v_mfma_f32_16x16x32_bf16 v[20:23], v[244:247], v[204:207], v[216:219]
	v_mfma_f32_16x16x32_bf16 v[20:23], v[150:153], v[208:211], v[20:23]
	s_barrier
	s_setprio 0
	s_mov_b64 s[8:9], 0
	v_mov_b64_e32 v[234:235], v[198:199]
	v_mov_b64_e32 v[236:237], v[226:227]
	v_mov_b32_e32 v198, v0
	v_mov_b32_e32 v226, v225
	v_mov_b64_e32 v[244:245], 0x100
	v_mov_b64_e32 v[246:247], 0xff

; #define PG8_WAIT_V(n) asm volatile("s_waitcnt vmcnt(" #n ")" ::: "memory")
; template <class Epi, bool ALIGN_EPI, bool SP2, class Hook>
; __device__ __forceinline__ void gemm_phase(LAS unsigned char* lds, const Gemm g, const StaticOrder& S, const Epi& E, Acc& acc, const bool fresh, const Hook& H, const int wave_id) {
;     ...
;         for (int t = t0; t < nt; t += 2) {
;             const bool last = (t == nt - 2);
;             const Src a1 = cA + (size_t)(t + 1) * kstep;
;             const Src a2 = last ? nA : cA + (size_t)(t + 2) * kstep, b2 = last ? nB : cB + (size_t)(t + 2) * kstep;
;             const Src a3 = a2 + kstep, b3 = b2 + kstep;
;             if (last && has_next) H(nxt);
;             if constexpr (SP2) {
;             PG8_TRIP_SP2(PG8_WAIT_V(8));
.LBB0_391:
	s_add_i32 s100, s56, 0xfffc0000
	v_add_u32_e32 v150, 0x10000, v148
	v_add_u32_e32 v151, 0x14000, v148
	ds_read_b128 v[132:135], v150
	ds_read_b128 v[136:139], v150 offset:1024
	ds_read_b128 v[140:143], v150 offset:2048
	ds_read_b128 v[152:155], v150 offset:3072
	ds_read_b128 v[156:159], v151
	ds_read_b128 v[160:163], v151 offset:1024
	ds_read_b128 v[164:167], v151 offset:2048
	ds_read_b128 v[168:171], v151 offset:3072
	s_add_i32 s12, s56, 0xfffc0080
	s_cmp_eq_u32 s29, 12
	s_cselect_b32 s60, s68, s12
	s_cselect_b32 s13, s5, s77
	s_cselect_b32 s12, s4, s76
	s_cselect_b32 s15, s7, s55
	s_cselect_b32 s14, s6, s54
	s_cselect_b32 s58, s69, s57
	s_cselect_b32 s16, s0, s8
	s_cselect_b32 s17, s1, s9
	s_cselect_b32 s18, s2, s10
	s_cselect_b32 s19, s3, s11
	s_or_b32 s59, s60, 0x80
	s_mov_b32 m0, s41
	s_nop 0
	buffer_load_dwordx4 v144, s[8:11], s100 offen lds
	s_mov_b32 m0, s33
	s_nop 0
	buffer_load_dwordx4 v146, s[8:11], s100 offen lds
	s_mov_b32 m0, s45
	ds_read_b128 v[172:175], v149
	ds_read_b128 v[176:179], v149 offset:1024
	ds_read_b128 v[180:183], v149 offset:2048
	ds_read_b128 v[184:187], v149 offset:3072
	ds_read_b128 v[188:191], v149 offset:4096
	ds_read_b128 v[212:215], v149 offset:5120
	ds_read_b128 v[216:219], v149 offset:6144
	ds_read_b128 v[228:231], v149 offset:7168
	buffer_load_dwordx4 v144, s[8:11], s56 offen lds
	s_mov_b32 m0, s46
	s_nop 0
	buffer_load_dwordx4 v146, s[8:11], s56 offen lds
	s_waitcnt vmcnt(8)
	s_waitcnt lgkmcnt(0)
	s_setprio 1
	s_barrier
	v_mfma_f32_16x16x32_bf16 v[120:123], v[132:135], v[172:175], v[120:123]
	v_mfma_f32_16x16x32_bf16 v[112:115], v[140:143], v[172:175], v[112:115]
	v_mfma_f32_16x16x32_bf16 v[100:103], v[132:135], v[180:183], v[100:103]
	v_mfma_f32_16x16x32_bf16 v[88:91], v[140:143], v[180:183], v[88:91]
	v_mfma_f32_16x16x32_bf16 v[68:71], v[132:135], v[188:191], v[68:71]
	v_mfma_f32_16x16x32_bf16 v[56:59], v[140:143], v[188:191], v[56:59]
	v_mfma_f32_16x16x32_bf16 v[36:39], v[132:135], v[216:219], v[36:39]
	v_mfma_f32_16x16x32_bf16 v[28:31], v[140:143], v[216:219], v[28:31]
	v_mfma_f32_16x16x32_bf16 v[120:123], v[136:139], v[176:179], v[120:123]
	v_mfma_f32_16x16x32_bf16 v[112:115], v[152:155], v[176:179], v[112:115]
	v_mfma_f32_16x16x32_bf16 v[100:103], v[136:139], v[184:187], v[100:103]
	v_mfma_f32_16x16x32_bf16 v[88:91], v[152:155], v[184:187], v[88:91]
	v_mfma_f32_16x16x32_bf16 v[68:71], v[136:139], v[212:215], v[68:71]
	v_mfma_f32_16x16x32_bf16 v[56:59], v[152:155], v[212:215], v[56:59]
	v_mfma_f32_16x16x32_bf16 v[36:39], v[136:139], v[228:231], v[36:39]
	v_mfma_f32_16x16x32_bf16 v[28:31], v[152:155], v[228:231], v[28:31]
	v_mfma_f32_16x16x32_bf16 v[128:131], v[156:159], v[172:175], v[128:131]
	v_mfma_f32_16x16x32_bf16 v[124:127], v[164:167], v[172:175], v[124:127]
	v_mfma_f32_16x16x32_bf16 v[116:119], v[156:159], v[180:183], v[116:119]
	v_mfma_f32_16x16x32_bf16 v[108:111], v[164:167], v[180:183], v[108:111]
	v_mfma_f32_16x16x32_bf16 v[92:95], v[156:159], v[188:191], v[92:95]
	v_mfma_f32_16x16x32_bf16 v[80:83], v[164:167], v[188:191], v[80:83]
	v_mfma_f32_16x16x32_bf16 v[64:67], v[156:159], v[216:219], v[64:67]
	v_mfma_f32_16x16x32_bf16 v[48:51], v[164:167], v[216:219], v[48:51]
	v_mfma_f32_16x16x32_bf16 v[128:131], v[160:163], v[176:179], v[128:131]
	v_mfma_f32_16x16x32_bf16 v[124:127], v[168:171], v[176:179], v[124:127]
	v_mfma_f32_16x16x32_bf16 v[116:119], v[160:163], v[184:187], v[116:119]
	v_mfma_f32_16x16x32_bf16 v[108:111], v[168:171], v[184:187], v[108:111]
	v_mfma_f32_16x16x32_bf16 v[92:95], v[160:163], v[212:215], v[92:95]
	v_mfma_f32_16x16x32_bf16 v[80:83], v[168:171], v[212:215], v[80:83]
	v_mfma_f32_16x16x32_bf16 v[64:67], v[160:163], v[228:231], v[64:67]
	v_mfma_f32_16x16x32_bf16 v[48:51], v[168:171], v[228:231], v[48:51]
	s_barrier
	s_setprio 0
	s_mov_b32 m0, s92
	ds_read_b128 v[172:175], v149 offset:16384
	ds_read_b128 v[176:179], v149 offset:17408
	ds_read_b128 v[180:183], v149 offset:18432
	ds_read_b128 v[184:187], v149 offset:19456
	ds_read_b128 v[188:191], v149 offset:20480
	ds_read_b128 v[212:215], v149 offset:21504
	ds_read_b128 v[216:219], v149 offset:22528
	ds_read_b128 v[228:231], v149 offset:23552
	buffer_load_dwordx4 v145, s[12:15], s58 offen lds
	s_mov_b32 m0, s93
	s_add_i32 s61, s58, 0x40000
	buffer_load_dwordx4 v147, s[12:15], s58 offen lds
	s_mov_b32 m0, s94
	s_nop 0
	buffer_load_dwordx4 v145, s[12:15], s61 offen lds
	s_mov_b32 m0, s95
	s_nop 0
	buffer_load_dwordx4 v147, s[12:15], s61 offen lds
	s_waitcnt vmcnt(6)
	s_waitcnt lgkmcnt(0)
	s_setprio 1
	s_barrier
	v_mfma_f32_16x16x32_bf16 v[72:75], v[132:135], v[172:175], v[72:75]
	v_mfma_f32_16x16x32_bf16 v[60:63], v[140:143], v[172:175], v[60:63]
	v_mfma_f32_16x16x32_bf16 v[40:43], v[132:135], v[180:183], v[40:43]
	v_mfma_f32_16x16x32_bf16 v[32:35], v[140:143], v[180:183], v[32:35]
	v_mfma_f32_16x16x32_bf16 v[16:19], v[132:135], v[188:191], v[16:19]
	v_mfma_f32_16x16x32_bf16 v[12:15], v[140:143], v[188:191], v[12:15]
	v_mfma_f32_16x16x32_bf16 v[8:11], v[132:135], v[216:219], v[8:11]
	v_mfma_f32_16x16x32_bf16 v[2:5], v[140:143], v[216:219], v[4:7]
	v_mfma_f32_16x16x32_bf16 v[72:75], v[136:139], v[176:179], v[72:75]
	v_mfma_f32_16x16x32_bf16 v[60:63], v[152:155], v[176:179], v[60:63]
	v_mfma_f32_16x16x32_bf16 v[40:43], v[136:139], v[184:187], v[40:43]
	v_mfma_f32_16x16x32_bf16 v[32:35], v[152:155], v[184:187], v[32:35]
	v_mfma_f32_16x16x32_bf16 v[16:19], v[136:139], v[212:215], v[16:19]
	v_mfma_f32_16x16x32_bf16 v[12:15], v[152:155], v[212:215], v[12:15]
	v_mfma_f32_16x16x32_bf16 v[8:11], v[136:139], v[228:231], v[8:11]
	v_mfma_f32_16x16x32_bf16 v[2:5], v[152:155], v[228:231], v[2:5]
	v_mfma_f32_16x16x32_bf16 v[96:99], v[156:159], v[172:175], v[96:99]
	v_mfma_f32_16x16x32_bf16 v[104:107], v[164:167], v[172:175], v[104:107]
	v_mfma_f32_16x16x32_bf16 v[84:87], v[156:159], v[180:183], v[84:87]
	v_mfma_f32_16x16x32_bf16 v[76:79], v[164:167], v[180:183], v[76:79]
	v_mfma_f32_16x16x32_bf16 v[52:55], v[156:159], v[188:191], v[52:55]
	v_mfma_f32_16x16x32_bf16 v[44:47], v[164:167], v[188:191], v[44:47]
	v_mfma_f32_16x16x32_bf16 v[24:27], v[156:159], v[216:219], v[24:27]
	v_mfma_f32_16x16x32_bf16 v[20:23], v[164:167], v[216:219], v[20:23]
	v_mfma_f32_16x16x32_bf16 v[96:99], v[160:163], v[176:179], v[96:99]
	v_mfma_f32_16x16x32_bf16 v[104:107], v[168:171], v[176:179], v[104:107]
	v_mfma_f32_16x16x32_bf16 v[84:87], v[160:163], v[184:187], v[84:87]
	v_mfma_f32_16x16x32_bf16 v[76:79], v[168:171], v[184:187], v[76:79]
	v_mfma_f32_16x16x32_bf16 v[52:55], v[160:163], v[212:215], v[52:55]
	v_mfma_f32_16x16x32_bf16 v[44:47], v[168:171], v[212:215], v[44:47]
	v_mfma_f32_16x16x32_bf16 v[24:27], v[160:163], v[228:231], v[24:27]
	v_mfma_f32_16x16x32_bf16 v[20:23], v[168:171], v[228:231], v[20:23]
	s_barrier
; #define PG8_WAIT_V(n) asm volatile("s_waitcnt vmcnt(" #n ")" ::: "memory")
; template <class Epi, bool ALIGN_EPI, bool SP2, class Hook>
; __device__ __forceinline__ void gemm_phase(LAS unsigned char* lds, const Gemm g, const StaticOrder& S, const Epi& E, Acc& acc, const bool fresh, const Hook& H, const int wave_id) {
;     ...
;         for (int t = t0; t < nt; t += 2) {
;             const bool last = (t == nt - 2);
;             const Src a1 = cA + (size_t)(t + 1) * kstep;
;             const Src a2 = last ? nA : cA + (size_t)(t + 2) * kstep, b2 = last ? nB : cB + (size_t)(t + 2) * kstep;
;             const Src a3 = a2 + kstep, b3 = b2 + kstep;
;             if (last && has_next) H(nxt);
;             if constexpr (SP2) {
;             PG8_TRIP_SP2(PG8_WAIT_V(8));
	s_setprio 0
	s_mov_b32 m0, s44
	s_nop 0
	buffer_load_dwordx4 v144, s[16:19], s60 offen lds
	s_mov_b32 m0, s36
	s_nop 0
	buffer_load_dwordx4 v146, s[16:19], s60 offen lds
	v_add_u32_e32 v152, 0x18000, v148
	v_add_u32_e32 v153, 0x1c000, v148
	ds_read_b128 v[132:135], v152
	ds_read_b128 v[136:139], v152 offset:1024
	ds_read_b128 v[140:143], v152 offset:2048
	ds_read_b128 v[154:157], v152 offset:3072
	ds_read_b128 v[158:161], v153
	ds_read_b128 v[162:165], v153 offset:1024
	ds_read_b128 v[166:169], v153 offset:2048
	ds_read_b128 v[170:173], v153 offset:3072
	s_add_i32 s60, s60, 0x40000
	s_mov_b32 m0, s37
	ds_read_b128 v[174:177], v149 offset:32768
	ds_read_b128 v[178:181], v149 offset:33792
	ds_read_b128 v[182:185], v149 offset:34816
	ds_read_b128 v[186:189], v149 offset:35840
	ds_read_b128 v[190:193], v149 offset:36864
	ds_read_b128 v[212:215], v149 offset:37888
	ds_read_b128 v[216:219], v149 offset:38912
	ds_read_b128 v[228:231], v149 offset:39936
	buffer_load_dwordx4 v144, s[16:19], s60 offen lds
	s_mov_b32 m0, s38
	s_nop 0
	buffer_load_dwordx4 v146, s[16:19], s60 offen lds
	s_waitcnt vmcnt(8)
	s_waitcnt lgkmcnt(0)
	s_setprio 1
	s_barrier
	v_mfma_f32_16x16x32_bf16 v[120:123], v[132:135], v[174:177], v[120:123]
	v_mfma_f32_16x16x32_bf16 v[112:115], v[140:143], v[174:177], v[112:115]
	v_mfma_f32_16x16x32_bf16 v[100:103], v[132:135], v[182:185], v[100:103]
	v_mfma_f32_16x16x32_bf16 v[88:91], v[140:143], v[182:185], v[88:91]
	v_mfma_f32_16x16x32_bf16 v[68:71], v[132:135], v[190:193], v[68:71]
	v_mfma_f32_16x16x32_bf16 v[56:59], v[140:143], v[190:193], v[56:59]
	v_mfma_f32_16x16x32_bf16 v[36:39], v[132:135], v[216:219], v[36:39]
	v_mfma_f32_16x16x32_bf16 v[28:31], v[140:143], v[216:219], v[28:31]
	v_mfma_f32_16x16x32_bf16 v[120:123], v[136:139], v[178:181], v[120:123]
	v_mfma_f32_16x16x32_bf16 v[112:115], v[154:157], v[178:181], v[112:115]
	v_mfma_f32_16x16x32_bf16 v[100:103], v[136:139], v[186:189], v[100:103]
	v_mfma_f32_16x16x32_bf16 v[88:91], v[154:157], v[186:189], v[88:91]
	v_mfma_f32_16x16x32_bf16 v[68:71], v[136:139], v[212:215], v[68:71]
	v_mfma_f32_16x16x32_bf16 v[56:59], v[154:157], v[212:215], v[56:59]
	v_mfma_f32_16x16x32_bf16 v[36:39], v[136:139], v[228:231], v[36:39]
	v_mfma_f32_16x16x32_bf16 v[28:31], v[154:157], v[228:231], v[28:31]
	v_mfma_f32_16x16x32_bf16 v[128:131], v[158:161], v[174:177], v[128:131]
	v_mfma_f32_16x16x32_bf16 v[124:127], v[166:169], v[174:177], v[124:127]
	v_mfma_f32_16x16x32_bf16 v[116:119], v[158:161], v[182:185], v[116:119]
	v_mfma_f32_16x16x32_bf16 v[108:111], v[166:169], v[182:185], v[108:111]
	v_mfma_f32_16x16x32_bf16 v[92:95], v[158:161], v[190:193], v[92:95]
	v_mfma_f32_16x16x32_bf16 v[80:83], v[166:169], v[190:193], v[80:83]
	v_mfma_f32_16x16x32_bf16 v[64:67], v[158:161], v[216:219], v[64:67]
	v_mfma_f32_16x16x32_bf16 v[48:51], v[166:169], v[216:219], v[48:51]
	v_mfma_f32_16x16x32_bf16 v[128:131], v[162:165], v[178:181], v[128:131]
	v_mfma_f32_16x16x32_bf16 v[124:127], v[170:173], v[178:181], v[124:127]
	v_mfma_f32_16x16x32_bf16 v[116:119], v[162:165], v[186:189], v[116:119]
	v_mfma_f32_16x16x32_bf16 v[108:111], v[170:173], v[186:189], v[108:111]
	v_mfma_f32_16x16x32_bf16 v[92:95], v[162:165], v[212:215], v[92:95]
	v_mfma_f32_16x16x32_bf16 v[80:83], v[170:173], v[212:215], v[80:83]
	v_mfma_f32_16x16x32_bf16 v[64:67], v[162:165], v[228:231], v[64:67]
	v_mfma_f32_16x16x32_bf16 v[48:51], v[170:173], v[228:231], v[48:51]
	s_barrier
	s_setprio 0
	s_mov_b32 m0, s39
	s_or_b32 s60, s58, 0x80
	ds_read_b128 v[174:177], v149 offset:49152
	ds_read_b128 v[178:181], v149 offset:50176
	ds_read_b128 v[182:185], v149 offset:51200
	ds_read_b128 v[186:189], v149 offset:52224
	ds_read_b128 v[190:193], v149 offset:53248
	ds_read_b128 v[212:215], v149 offset:54272
	ds_read_b128 v[216:219], v149 offset:55296
	ds_read_b128 v[228:231], v149 offset:56320
	buffer_load_dwordx4 v145, s[12:15], s60 offen lds
	s_mov_b32 m0, s40
	s_add_i32 s58, s58, 0x40080
	buffer_load_dwordx4 v147, s[12:15], s60 offen lds
	s_mov_b32 m0, s43
	s_nop 0
	buffer_load_dwordx4 v145, s[12:15], s58 offen lds
	s_mov_b32 m0, s42
	s_nop 0
	buffer_load_dwordx4 v147, s[12:15], s58 offen lds
	s_waitcnt vmcnt(6)
	s_waitcnt lgkmcnt(0)
	s_setprio 1
	s_barrier
	v_mfma_f32_16x16x32_bf16 v[72:75], v[132:135], v[174:177], v[72:75]
	v_mfma_f32_16x16x32_bf16 v[60:63], v[140:143], v[174:177], v[60:63]
	v_mfma_f32_16x16x32_bf16 v[40:43], v[132:135], v[182:185], v[40:43]
	v_mfma_f32_16x16x32_bf16 v[32:35], v[140:143], v[182:185], v[32:35]
	v_mfma_f32_16x16x32_bf16 v[16:19], v[132:135], v[190:193], v[16:19]
	v_mfma_f32_16x16x32_bf16 v[12:15], v[140:143], v[190:193], v[12:15]
	v_mfma_f32_16x16x32_bf16 v[6:9], v[132:135], v[216:219], v[8:11]
	v_mfma_f32_16x16x32_bf16 v[2:5], v[140:143], v[216:219], v[2:5]
	v_mfma_f32_16x16x32_bf16 v[72:75], v[136:139], v[178:181], v[72:75]
	v_mfma_f32_16x16x32_bf16 v[60:63], v[154:157], v[178:181], v[60:63]
	v_mfma_f32_16x16x32_bf16 v[40:43], v[136:139], v[186:189], v[40:43]
	v_mfma_f32_16x16x32_bf16 v[32:35], v[154:157], v[186:189], v[32:35]
	v_mfma_f32_16x16x32_bf16 v[16:19], v[136:139], v[212:215], v[16:19]
	v_mfma_f32_16x16x32_bf16 v[12:15], v[154:157], v[212:215], v[12:15]
	v_mfma_f32_16x16x32_bf16 v[8:11], v[136:139], v[228:231], v[6:9]
	v_mfma_f32_16x16x32_bf16 v[4:7], v[154:157], v[228:231], v[2:5]
	v_mfma_f32_16x16x32_bf16 v[96:99], v[158:161], v[174:177], v[96:99]
	v_mfma_f32_16x16x32_bf16 v[104:107], v[166:169], v[174:177], v[104:107]
	v_mfma_f32_16x16x32_bf16 v[84:87], v[158:161], v[182:185], v[84:87]
	v_mfma_f32_16x16x32_bf16 v[76:79], v[166:169], v[182:185], v[76:79]
	v_mfma_f32_16x16x32_bf16 v[52:55], v[158:161], v[190:193], v[52:55]
	v_mfma_f32_16x16x32_bf16 v[44:47], v[166:169], v[190:193], v[44:47]
	v_mfma_f32_16x16x32_bf16 v[24:27], v[158:161], v[216:219], v[24:27]
	v_mfma_f32_16x16x32_bf16 v[20:23], v[166:169], v[216:219], v[20:23]
	v_mfma_f32_16x16x32_bf16 v[96:99], v[162:165], v[178:181], v[96:99]
	v_mfma_f32_16x16x32_bf16 v[104:107], v[170:173], v[178:181], v[104:107]
	v_mfma_f32_16x16x32_bf16 v[84:87], v[162:165], v[186:189], v[84:87]
	v_mfma_f32_16x16x32_bf16 v[76:79], v[170:173], v[186:189], v[76:79]
	v_mfma_f32_16x16x32_bf16 v[52:55], v[162:165], v[212:215], v[52:55]
	v_mfma_f32_16x16x32_bf16 v[44:47], v[170:173], v[212:215], v[44:47]
	v_mfma_f32_16x16x32_bf16 v[24:27], v[162:165], v[228:231], v[24:27]
	v_mfma_f32_16x16x32_bf16 v[20:23], v[170:173], v[228:231], v[20:23]
	s_barrier
	s_setprio 0
	s_add_i32 s29, s29, 2
	s_addk_i32 s56, 0x100
	s_addk_i32 s57, 0x100
	s_cmp_gt_u32 s29, 13
	s_cbranch_scc0 .LBB0_391
	s_mov_b32 m0, s41
	s_nop 0
	buffer_load_dwordx4 v144, s[16:19], s59 offen lds
	s_mov_b32 m0, s33
	s_nop 0
	buffer_load_dwordx4 v146, s[16:19], s59 offen lds
	v_readlane_b32 s8, v251, 45
	v_readlane_b32 s9, v251, 46
	s_and_b64 vcc, exec, s[8:9]
	s_cbranch_vccz .LBB0_394
	s_barrier

; #define PG8_WAIT_V(n) asm volatile("s_waitcnt vmcnt(" #n ")" ::: "memory")
; template <class Epi, bool ALIGN_EPI, bool SP2, class Hook>
; __device__ __forceinline__ void gemm_phase(LAS unsigned char* lds, const Gemm g, const StaticOrder& S, const Epi& E, Acc& acc, const bool fresh, const Hook& H, const int wave_id) {
;     ...
;         for (int t = t0; t < nt; t += 2) {
;             const bool last = (t == nt - 2);
;             const Src a1 = cA + (size_t)(t + 1) * kstep;
;             const Src a2 = last ? nA : cA + (size_t)(t + 2) * kstep, b2 = last ? nB : cB + (size_t)(t + 2) * kstep;
;             const Src a3 = a2 + kstep, b3 = b2 + kstep;
;             if (last && has_next) H(nxt);
;             if constexpr (SP2) {
;             PG8_TRIP_SP2(PG8_WAIT_V(8));
.LBB0_903:
	s_add_i32 s100, s55, 0xfffe0000
	v_add_u32_e32 v70, 0x10000, v216
	v_add_u32_e32 v118, 0x14000, v216
	ds_read_b128 v[34:37], v70
	ds_read_b128 v[46:49], v70 offset:1024
	ds_read_b128 v[58:61], v70 offset:2048
	ds_read_b128 v[70:73], v70 offset:3072
	ds_read_b128 v[82:85], v118
	ds_read_b128 v[94:97], v118 offset:1024
	ds_read_b128 v[106:109], v118 offset:2048
	ds_read_b128 v[118:121], v118 offset:3072
	s_add_i32 s12, s55, 0xfffe0080
	s_cmp_eq_u32 s57, 4
	s_cselect_b32 s60, s53, s12
	s_cselect_b32 s13, s29, s77
	s_cselect_b32 s12, s28, s76
	s_cselect_b32 s15, s31, s35
	s_cselect_b32 s14, s30, s34
	s_cselect_b32 s58, s54, s56
	s_cselect_b32 s16, s2, s8
	s_cselect_b32 s17, s3, s9
	s_cselect_b32 s18, s26, s10
	s_cselect_b32 s19, s27, s11
	s_or_b32 s59, s60, 0x80
	s_mov_b32 m0, s41
	s_nop 0
	buffer_load_dwordx4 v0, s[8:11], s100 offen lds
	s_mov_b32 m0, s33
	s_nop 0
	buffer_load_dwordx4 v214, s[8:11], s100 offen lds
	s_mov_b32 m0, s45
	ds_read_b128 v[130:133], v217
	ds_read_b128 v[142:145], v217 offset:1024
	ds_read_b128 v[154:157], v217 offset:2048
	ds_read_b128 v[166:169], v217 offset:3072
	ds_read_b128 v[174:177], v217 offset:4096
	ds_read_b128 v[182:185], v217 offset:5120
	ds_read_b128 v[186:189], v217 offset:6144
	ds_read_b128 v[190:193], v217 offset:7168
	buffer_load_dwordx4 v0, s[8:11], s55 offen lds
	s_mov_b32 m0, s46
	s_nop 0
	buffer_load_dwordx4 v214, s[8:11], s55 offen lds
	s_waitcnt vmcnt(8)
	s_waitcnt lgkmcnt(0)
	s_setprio 1
	s_barrier
	v_mfma_f32_16x16x32_bf16 v[178:181], v[34:37], v[130:133], v[178:181]
	v_mfma_f32_16x16x32_bf16 v[170:173], v[58:61], v[130:133], v[170:173]
	v_mfma_f32_16x16x32_bf16 v[150:153], v[34:37], v[154:157], v[150:153]
	v_mfma_f32_16x16x32_bf16 v[146:149], v[58:61], v[154:157], v[146:149]
	v_mfma_f32_16x16x32_bf16 v[126:129], v[34:37], v[174:177], v[126:129]
	v_mfma_f32_16x16x32_bf16 v[122:125], v[58:61], v[174:177], v[122:125]
	v_mfma_f32_16x16x32_bf16 v[102:105], v[34:37], v[186:189], v[102:105]
	v_mfma_f32_16x16x32_bf16 v[98:101], v[58:61], v[186:189], v[98:101]
	v_mfma_f32_16x16x32_bf16 v[178:181], v[46:49], v[142:145], v[178:181]
	v_mfma_f32_16x16x32_bf16 v[170:173], v[70:73], v[142:145], v[170:173]
	v_mfma_f32_16x16x32_bf16 v[150:153], v[46:49], v[166:169], v[150:153]
	v_mfma_f32_16x16x32_bf16 v[146:149], v[70:73], v[166:169], v[146:149]
	v_mfma_f32_16x16x32_bf16 v[126:129], v[46:49], v[182:185], v[126:129]
	v_mfma_f32_16x16x32_bf16 v[122:125], v[70:73], v[182:185], v[122:125]
	v_mfma_f32_16x16x32_bf16 v[102:105], v[46:49], v[190:193], v[102:105]
	v_mfma_f32_16x16x32_bf16 v[98:101], v[70:73], v[190:193], v[98:101]
	v_mfma_f32_16x16x32_bf16 v[162:165], v[82:85], v[130:133], v[162:165]
	v_mfma_f32_16x16x32_bf16 v[138:141], v[82:85], v[154:157], v[138:141]
	v_mfma_f32_16x16x32_bf16 v[134:137], v[106:109], v[154:157], v[134:137]
	v_mfma_f32_16x16x32_bf16 v[114:117], v[82:85], v[174:177], v[114:117]
	v_mfma_f32_16x16x32_bf16 v[110:113], v[106:109], v[174:177], v[110:113]
	v_mfma_f32_16x16x32_bf16 v[90:93], v[82:85], v[186:189], v[90:93]
	v_mfma_f32_16x16x32_bf16 v[86:89], v[106:109], v[186:189], v[86:89]
	v_mfma_f32_16x16x32_bf16 v[162:165], v[94:97], v[142:145], v[162:165]
	v_mfma_f32_16x16x32_bf16 v[130:133], v[106:109], v[130:133], v[158:161]
	v_mfma_f32_16x16x32_bf16 v[138:141], v[94:97], v[166:169], v[138:141]
	v_mfma_f32_16x16x32_bf16 v[134:137], v[118:121], v[166:169], v[134:137]
	v_mfma_f32_16x16x32_bf16 v[114:117], v[94:97], v[182:185], v[114:117]
	v_mfma_f32_16x16x32_bf16 v[110:113], v[118:121], v[182:185], v[110:113]
	v_mfma_f32_16x16x32_bf16 v[90:93], v[94:97], v[190:193], v[90:93]
	v_mfma_f32_16x16x32_bf16 v[86:89], v[118:121], v[190:193], v[86:89]
	v_mfma_f32_16x16x32_bf16 v[130:133], v[118:121], v[142:145], v[130:133]
	s_barrier
	s_setprio 0
	s_mov_b32 m0, s92
	ds_read_b128 v[142:145], v217 offset:16384
	ds_read_b128 v[154:157], v217 offset:17408
	ds_read_b128 v[158:161], v217 offset:18432
	ds_read_b128 v[166:169], v217 offset:19456
	ds_read_b128 v[174:177], v217 offset:20480
	ds_read_b128 v[182:185], v217 offset:21504
	ds_read_b128 v[186:189], v217 offset:22528
	ds_read_b128 v[190:193], v217 offset:23552
	buffer_load_dwordx4 v199, s[12:15], s58 offen lds
	s_mov_b32 m0, s93
	s_add_i32 s61, s58, 0x20000
	buffer_load_dwordx4 v215, s[12:15], s58 offen lds
	s_mov_b32 m0, s94
	s_nop 0
	buffer_load_dwordx4 v199, s[12:15], s61 offen lds
	s_mov_b32 m0, s95
	s_nop 0
	buffer_load_dwordx4 v215, s[12:15], s61 offen lds
	s_waitcnt vmcnt(6)
	s_waitcnt lgkmcnt(0)
	s_setprio 1
	s_barrier
	v_mfma_f32_16x16x32_bf16 v[78:81], v[34:37], v[142:145], v[78:81]
	v_mfma_f32_16x16x32_bf16 v[74:77], v[58:61], v[142:145], v[74:77]
	v_mfma_f32_16x16x32_bf16 v[54:57], v[34:37], v[158:161], v[54:57]
	v_mfma_f32_16x16x32_bf16 v[50:53], v[58:61], v[158:161], v[50:53]
	v_mfma_f32_16x16x32_bf16 v[30:33], v[34:37], v[174:177], v[30:33]
	v_mfma_f32_16x16x32_bf16 v[26:29], v[58:61], v[174:177], v[26:29]
	v_mfma_f32_16x16x32_bf16 v[14:17], v[34:37], v[186:189], v[14:17]
	v_mfma_f32_16x16x32_bf16 v[10:13], v[58:61], v[186:189], v[10:13]
	v_mfma_f32_16x16x32_bf16 v[78:81], v[46:49], v[154:157], v[78:81]
	v_mfma_f32_16x16x32_bf16 v[74:77], v[70:73], v[154:157], v[74:77]
	v_mfma_f32_16x16x32_bf16 v[54:57], v[46:49], v[166:169], v[54:57]
	v_mfma_f32_16x16x32_bf16 v[50:53], v[70:73], v[166:169], v[50:53]
	v_mfma_f32_16x16x32_bf16 v[30:33], v[46:49], v[182:185], v[30:33]
	v_mfma_f32_16x16x32_bf16 v[26:29], v[70:73], v[182:185], v[26:29]
	v_mfma_f32_16x16x32_bf16 v[14:17], v[46:49], v[190:193], v[14:17]
	v_mfma_f32_16x16x32_bf16 v[10:13], v[70:73], v[190:193], v[10:13]
	v_mfma_f32_16x16x32_bf16 v[42:45], v[82:85], v[158:161], v[42:45]
	v_mfma_f32_16x16x32_bf16 v[38:41], v[106:109], v[158:161], v[38:41]
	v_mfma_f32_16x16x32_bf16 v[22:25], v[82:85], v[174:177], v[22:25]
	v_mfma_f32_16x16x32_bf16 v[18:21], v[106:109], v[174:177], v[18:21]
	v_mfma_f32_16x16x32_bf16 v[6:9], v[82:85], v[186:189], v[6:9]
	v_mfma_f32_16x16x32_bf16 v[2:5], v[106:109], v[186:189], v[2:5]
	v_mfma_f32_16x16x32_bf16 v[34:37], v[82:85], v[142:145], v[66:69]
	v_mfma_f32_16x16x32_bf16 v[46:49], v[106:109], v[142:145], v[62:65]
	v_mfma_f32_16x16x32_bf16 v[42:45], v[94:97], v[166:169], v[42:45]
	v_mfma_f32_16x16x32_bf16 v[38:41], v[118:121], v[166:169], v[38:41]
	v_mfma_f32_16x16x32_bf16 v[22:25], v[94:97], v[182:185], v[22:25]
	v_mfma_f32_16x16x32_bf16 v[18:21], v[118:121], v[182:185], v[18:21]
	v_mfma_f32_16x16x32_bf16 v[6:9], v[94:97], v[190:193], v[6:9]
	v_mfma_f32_16x16x32_bf16 v[2:5], v[118:121], v[190:193], v[2:5]
	v_mfma_f32_16x16x32_bf16 v[34:37], v[94:97], v[154:157], v[34:37]
	v_mfma_f32_16x16x32_bf16 v[46:49], v[118:121], v[154:157], v[46:49]
	s_barrier
; #define PG8_WAIT_V(n) asm volatile("s_waitcnt vmcnt(" #n ")" ::: "memory")
; template <class Epi, bool ALIGN_EPI, bool SP2, class Hook>
; __device__ __forceinline__ void gemm_phase(LAS unsigned char* lds, const Gemm g, const StaticOrder& S, const Epi& E, Acc& acc, const bool fresh, const Hook& H, const int wave_id) {
;     ...
;         for (int t = t0; t < nt; t += 2) {
;             const bool last = (t == nt - 2);
;             const Src a1 = cA + (size_t)(t + 1) * kstep;
;             const Src a2 = last ? nA : cA + (size_t)(t + 2) * kstep, b2 = last ? nB : cB + (size_t)(t + 2) * kstep;
;             const Src a3 = a2 + kstep, b3 = b2 + kstep;
;             if (last && has_next) H(nxt);
;             if constexpr (SP2) {
;             PG8_TRIP_SP2(PG8_WAIT_V(8));
	s_setprio 0
	s_mov_b32 m0, s44
	s_nop 0
	buffer_load_dwordx4 v0, s[16:19], s60 offen lds
	s_mov_b32 m0, s36
	s_nop 0
	buffer_load_dwordx4 v214, s[16:19], s60 offen lds
	v_add_u32_e32 v70, 0x18000, v216
	v_add_u32_e32 v118, 0x1c000, v216
	ds_read_b128 v[58:61], v70
	ds_read_b128 v[62:65], v70 offset:1024
	ds_read_b128 v[66:69], v70 offset:2048
	ds_read_b128 v[70:73], v70 offset:3072
	ds_read_b128 v[82:85], v118
	ds_read_b128 v[94:97], v118 offset:1024
	ds_read_b128 v[106:109], v118 offset:2048
	ds_read_b128 v[118:121], v118 offset:3072
	s_add_i32 s60, s60, 0x20000
	s_mov_b32 m0, s37
	ds_read_b128 v[142:145], v217 offset:32768
	ds_read_b128 v[154:157], v217 offset:33792
	ds_read_b128 v[166:169], v217 offset:34816
	ds_read_b128 v[174:177], v217 offset:35840
	ds_read_b128 v[182:185], v217 offset:36864
	ds_read_b128 v[186:189], v217 offset:37888
	ds_read_b128 v[190:193], v217 offset:38912
	ds_read_b128 v[194:197], v217 offset:39936
	buffer_load_dwordx4 v0, s[16:19], s60 offen lds
	s_mov_b32 m0, s38
	s_nop 0
	buffer_load_dwordx4 v214, s[16:19], s60 offen lds
	s_waitcnt vmcnt(8)
	s_waitcnt lgkmcnt(0)
	s_setprio 1
	s_barrier
	v_mfma_f32_16x16x32_bf16 v[158:161], v[58:61], v[142:145], v[178:181]
	v_mfma_f32_16x16x32_bf16 v[178:181], v[62:65], v[154:157], v[158:161]
	v_mfma_f32_16x16x32_bf16 v[158:161], v[66:69], v[142:145], v[170:173]
	v_mfma_f32_16x16x32_bf16 v[150:153], v[58:61], v[166:169], v[150:153]
	v_mfma_f32_16x16x32_bf16 v[146:149], v[66:69], v[166:169], v[146:149]
	v_mfma_f32_16x16x32_bf16 v[126:129], v[58:61], v[182:185], v[126:129]
	v_mfma_f32_16x16x32_bf16 v[122:125], v[66:69], v[182:185], v[122:125]
	v_mfma_f32_16x16x32_bf16 v[102:105], v[58:61], v[190:193], v[102:105]
	v_mfma_f32_16x16x32_bf16 v[98:101], v[66:69], v[190:193], v[98:101]
	v_mfma_f32_16x16x32_bf16 v[170:173], v[70:73], v[154:157], v[158:161]
	v_mfma_f32_16x16x32_bf16 v[150:153], v[62:65], v[174:177], v[150:153]
	v_mfma_f32_16x16x32_bf16 v[146:149], v[70:73], v[174:177], v[146:149]
	v_mfma_f32_16x16x32_bf16 v[126:129], v[62:65], v[186:189], v[126:129]
	v_mfma_f32_16x16x32_bf16 v[122:125], v[70:73], v[186:189], v[122:125]
	v_mfma_f32_16x16x32_bf16 v[102:105], v[62:65], v[194:197], v[102:105]
	v_mfma_f32_16x16x32_bf16 v[98:101], v[70:73], v[194:197], v[98:101]
	v_mfma_f32_16x16x32_bf16 v[158:161], v[82:85], v[142:145], v[162:165]
	v_mfma_f32_16x16x32_bf16 v[130:133], v[106:109], v[142:145], v[130:133]
	v_mfma_f32_16x16x32_bf16 v[162:165], v[94:97], v[154:157], v[158:161]
	v_mfma_f32_16x16x32_bf16 v[158:161], v[118:121], v[154:157], v[130:133]
	v_mfma_f32_16x16x32_bf16 v[130:133], v[82:85], v[166:169], v[138:141]
	v_mfma_f32_16x16x32_bf16 v[138:141], v[94:97], v[174:177], v[130:133]
	v_mfma_f32_16x16x32_bf16 v[130:133], v[106:109], v[166:169], v[134:137]
	v_mfma_f32_16x16x32_bf16 v[114:117], v[82:85], v[182:185], v[114:117]
	v_mfma_f32_16x16x32_bf16 v[110:113], v[106:109], v[182:185], v[110:113]
	v_mfma_f32_16x16x32_bf16 v[90:93], v[82:85], v[190:193], v[90:93]
	v_mfma_f32_16x16x32_bf16 v[86:89], v[106:109], v[190:193], v[86:89]
	v_mfma_f32_16x16x32_bf16 v[134:137], v[118:121], v[174:177], v[130:133]
	v_mfma_f32_16x16x32_bf16 v[114:117], v[94:97], v[186:189], v[114:117]
	v_mfma_f32_16x16x32_bf16 v[110:113], v[118:121], v[186:189], v[110:113]
	v_mfma_f32_16x16x32_bf16 v[90:93], v[94:97], v[194:197], v[90:93]
	v_mfma_f32_16x16x32_bf16 v[86:89], v[118:121], v[194:197], v[86:89]
	s_barrier
	s_setprio 0
	s_mov_b32 m0, s39
	s_or_b32 s60, s58, 0x80
	ds_read_b128 v[130:133], v217 offset:49152
	ds_read_b128 v[142:145], v217 offset:50176
	ds_read_b128 v[154:157], v217 offset:51200
	ds_read_b128 v[166:169], v217 offset:52224
	ds_read_b128 v[174:177], v217 offset:53248
	ds_read_b128 v[182:185], v217 offset:54272
	ds_read_b128 v[186:189], v217 offset:55296
	ds_read_b128 v[190:193], v217 offset:56320
	buffer_load_dwordx4 v199, s[12:15], s60 offen lds
	s_mov_b32 m0, s40
	s_add_i32 s58, s58, 0x20080
	buffer_load_dwordx4 v215, s[12:15], s60 offen lds
	s_mov_b32 m0, s43
	s_nop 0
	buffer_load_dwordx4 v199, s[12:15], s58 offen lds
	s_mov_b32 m0, s42
	s_nop 0
	buffer_load_dwordx4 v215, s[12:15], s58 offen lds
	s_waitcnt vmcnt(6)
	s_waitcnt lgkmcnt(0)
	s_setprio 1
	s_barrier
	v_mfma_f32_16x16x32_bf16 v[78:81], v[58:61], v[130:133], v[78:81]
	v_mfma_f32_16x16x32_bf16 v[74:77], v[66:69], v[130:133], v[74:77]
	v_mfma_f32_16x16x32_bf16 v[54:57], v[58:61], v[154:157], v[54:57]
	v_mfma_f32_16x16x32_bf16 v[50:53], v[66:69], v[154:157], v[50:53]
	v_mfma_f32_16x16x32_bf16 v[30:33], v[58:61], v[174:177], v[30:33]
	v_mfma_f32_16x16x32_bf16 v[26:29], v[66:69], v[174:177], v[26:29]
	v_mfma_f32_16x16x32_bf16 v[14:17], v[58:61], v[186:189], v[14:17]
	v_mfma_f32_16x16x32_bf16 v[10:13], v[66:69], v[186:189], v[10:13]
	v_mfma_f32_16x16x32_bf16 v[78:81], v[62:65], v[142:145], v[78:81]
	v_mfma_f32_16x16x32_bf16 v[74:77], v[70:73], v[142:145], v[74:77]
	v_mfma_f32_16x16x32_bf16 v[54:57], v[62:65], v[166:169], v[54:57]
	v_mfma_f32_16x16x32_bf16 v[50:53], v[70:73], v[166:169], v[50:53]
	v_mfma_f32_16x16x32_bf16 v[30:33], v[62:65], v[182:185], v[30:33]
	v_mfma_f32_16x16x32_bf16 v[26:29], v[70:73], v[182:185], v[26:29]
	v_mfma_f32_16x16x32_bf16 v[14:17], v[62:65], v[190:193], v[14:17]
	v_mfma_f32_16x16x32_bf16 v[10:13], v[70:73], v[190:193], v[10:13]
	v_mfma_f32_16x16x32_bf16 v[34:37], v[82:85], v[130:133], v[34:37]
	v_mfma_f32_16x16x32_bf16 v[66:69], v[94:97], v[142:145], v[34:37]
	v_mfma_f32_16x16x32_bf16 v[34:37], v[106:109], v[130:133], v[46:49]
	v_mfma_f32_16x16x32_bf16 v[62:65], v[118:121], v[142:145], v[34:37]
	v_mfma_f32_16x16x32_bf16 v[34:37], v[82:85], v[154:157], v[42:45]
	v_mfma_f32_16x16x32_bf16 v[42:45], v[94:97], v[166:169], v[34:37]
	v_mfma_f32_16x16x32_bf16 v[34:37], v[106:109], v[154:157], v[38:41]
	v_mfma_f32_16x16x32_bf16 v[22:25], v[82:85], v[174:177], v[22:25]
	v_mfma_f32_16x16x32_bf16 v[18:21], v[106:109], v[174:177], v[18:21]
	v_mfma_f32_16x16x32_bf16 v[6:9], v[82:85], v[186:189], v[6:9]
	v_mfma_f32_16x16x32_bf16 v[2:5], v[106:109], v[186:189], v[2:5]
	v_mfma_f32_16x16x32_bf16 v[38:41], v[118:121], v[166:169], v[34:37]
	v_mfma_f32_16x16x32_bf16 v[22:25], v[94:97], v[182:185], v[22:25]
	v_mfma_f32_16x16x32_bf16 v[18:21], v[118:121], v[182:185], v[18:21]
	v_mfma_f32_16x16x32_bf16 v[6:9], v[94:97], v[190:193], v[6:9]
	v_mfma_f32_16x16x32_bf16 v[2:5], v[118:121], v[190:193], v[2:5]
	s_barrier
	s_setprio 0
	s_add_i32 s57, s57, 2
	s_addk_i32 s55, 0x100
	s_addk_i32 s56, 0x100
	s_cmp_gt_u32 s57, 5
	s_cbranch_scc0 .LBB0_903
	s_mov_b32 m0, s41
	s_nop 0
	buffer_load_dwordx4 v0, s[16:19], s59 offen lds
	s_mov_b32 m0, s33
	s_nop 0
	buffer_load_dwordx4 v214, s[16:19], s59 offen lds
	v_readlane_b32 s8, v251, 45
	v_readlane_b32 s9, v251, 46
	s_and_b64 vcc, exec, s[8:9]
	s_cbranch_vccz .LBB0_906
	s_barrier

; #define PG8_WAIT_V(n) asm volatile("s_waitcnt vmcnt(" #n ")" ::: "memory")
; template <class Epi, bool ALIGN_EPI, bool SP2, class Hook>
; __device__ __forceinline__ void gemm_phase(LAS unsigned char* lds, const Gemm g, const StaticOrder& S, const Epi& E, Acc& acc, const bool fresh, const Hook& H, const int wave_id) {
;     ...
;         for (int t = t0; t < nt; t += 2) {
;             const bool last = (t == nt - 2);
;             const Src a1 = cA + (size_t)(t + 1) * kstep;
;             const Src a2 = last ? nA : cA + (size_t)(t + 2) * kstep, b2 = last ? nB : cB + (size_t)(t + 2) * kstep;
;             const Src a3 = a2 + kstep, b3 = b2 + kstep;
;             if (last && has_next) H(nxt);
;             if constexpr (SP2) {
;             PG8_TRIP_SP2(PG8_WAIT_V(8));
.LBB0_1235:
	s_add_i32 s100, s2, 0xfffc0000
	v_add_u32_e32 v142, 0x10000, v161
	v_add_u32_e32 v163, 0x14000, v161
	ds_read_b128 v[130:133], v142
	ds_read_b128 v[134:137], v142 offset:1024
	ds_read_b128 v[138:141], v142 offset:2048
	ds_read_b128 v[142:145], v142 offset:3072
	ds_read_b128 v[146:149], v163
	ds_read_b128 v[150:153], v163 offset:1024
	ds_read_b128 v[154:157], v163 offset:2048
	ds_read_b128 v[164:167], v163 offset:3072
	s_add_i32 s16, s2, 0xfffc0080
	s_cmp_eq_u32 s59, 12
	s_cselect_b32 s62, s55, s16
	s_cselect_b32 s17, s31, s9
	s_cselect_b32 s16, s30, s8
	s_cselect_b32 s19, s35, s51
	s_cselect_b32 s18, s34, s50
	s_cselect_b32 s60, s56, s3
	s_cselect_b32 s20, s26, s12
	s_cselect_b32 s21, s27, s13
	s_cselect_b32 s22, s28, s14
	s_cselect_b32 s23, s29, s15
	s_or_b32 s61, s62, 0x80
	s_mov_b32 m0, s41
	s_nop 0
	buffer_load_dwordx4 v0, s[12:15], s100 offen lds
	s_mov_b32 m0, s33
	s_nop 0
	buffer_load_dwordx4 v159, s[12:15], s100 offen lds
	s_mov_b32 m0, s45
	ds_read_b128 v[168:171], v162
	ds_read_b128 v[172:175], v162 offset:1024
	ds_read_b128 v[176:179], v162 offset:2048
	ds_read_b128 v[180:183], v162 offset:3072
	ds_read_b128 v[184:187], v162 offset:4096
	ds_read_b128 v[188:191], v162 offset:5120
	ds_read_b128 v[192:195], v162 offset:6144
	ds_read_b128 v[200:203], v162 offset:7168
	buffer_load_dwordx4 v0, s[12:15], s2 offen lds
	s_mov_b32 m0, s46
	s_nop 0
	buffer_load_dwordx4 v159, s[12:15], s2 offen lds
	s_waitcnt vmcnt(8)
	s_waitcnt lgkmcnt(0)
	s_setprio 1
	s_barrier
	v_mfma_f32_16x16x32_bf16 v[126:129], v[130:133], v[168:171], v[126:129]
	v_mfma_f32_16x16x32_bf16 v[122:125], v[138:141], v[168:171], v[122:125]
	v_mfma_f32_16x16x32_bf16 v[110:113], v[130:133], v[176:179], v[110:113]
	v_mfma_f32_16x16x32_bf16 v[106:109], v[138:141], v[176:179], v[106:109]
	v_mfma_f32_16x16x32_bf16 v[94:97], v[130:133], v[184:187], v[94:97]
	v_mfma_f32_16x16x32_bf16 v[90:93], v[138:141], v[184:187], v[90:93]
	v_mfma_f32_16x16x32_bf16 v[78:81], v[130:133], v[192:195], v[78:81]
	v_mfma_f32_16x16x32_bf16 v[74:77], v[138:141], v[192:195], v[74:77]
	v_mfma_f32_16x16x32_bf16 v[126:129], v[134:137], v[172:175], v[126:129]
	v_mfma_f32_16x16x32_bf16 v[122:125], v[142:145], v[172:175], v[122:125]
	v_mfma_f32_16x16x32_bf16 v[110:113], v[134:137], v[180:183], v[110:113]
	v_mfma_f32_16x16x32_bf16 v[106:109], v[142:145], v[180:183], v[106:109]
	v_mfma_f32_16x16x32_bf16 v[94:97], v[134:137], v[188:191], v[94:97]
	v_mfma_f32_16x16x32_bf16 v[90:93], v[142:145], v[188:191], v[90:93]
	v_mfma_f32_16x16x32_bf16 v[78:81], v[134:137], v[200:203], v[78:81]
	v_mfma_f32_16x16x32_bf16 v[74:77], v[142:145], v[200:203], v[74:77]
	v_mfma_f32_16x16x32_bf16 v[118:121], v[146:149], v[168:171], v[118:121]
	v_mfma_f32_16x16x32_bf16 v[114:117], v[154:157], v[168:171], v[114:117]
	v_mfma_f32_16x16x32_bf16 v[102:105], v[146:149], v[176:179], v[102:105]
	v_mfma_f32_16x16x32_bf16 v[98:101], v[154:157], v[176:179], v[98:101]
	v_mfma_f32_16x16x32_bf16 v[86:89], v[146:149], v[184:187], v[86:89]
	v_mfma_f32_16x16x32_bf16 v[82:85], v[154:157], v[184:187], v[82:85]
	v_mfma_f32_16x16x32_bf16 v[70:73], v[146:149], v[192:195], v[70:73]
	v_mfma_f32_16x16x32_bf16 v[66:69], v[154:157], v[192:195], v[66:69]
	v_mfma_f32_16x16x32_bf16 v[118:121], v[150:153], v[172:175], v[118:121]
	v_mfma_f32_16x16x32_bf16 v[114:117], v[164:167], v[172:175], v[114:117]
	v_mfma_f32_16x16x32_bf16 v[102:105], v[150:153], v[180:183], v[102:105]
	v_mfma_f32_16x16x32_bf16 v[98:101], v[164:167], v[180:183], v[98:101]
	v_mfma_f32_16x16x32_bf16 v[86:89], v[150:153], v[188:191], v[86:89]
	v_mfma_f32_16x16x32_bf16 v[82:85], v[164:167], v[188:191], v[82:85]
	v_mfma_f32_16x16x32_bf16 v[70:73], v[150:153], v[200:203], v[70:73]
	v_mfma_f32_16x16x32_bf16 v[66:69], v[164:167], v[200:203], v[66:69]
	s_barrier
	s_setprio 0
	s_mov_b32 m0, s92
	ds_read_b128 v[168:171], v162 offset:16384
	ds_read_b128 v[172:175], v162 offset:17408
	ds_read_b128 v[176:179], v162 offset:18432
	ds_read_b128 v[180:183], v162 offset:19456
	ds_read_b128 v[184:187], v162 offset:20480
	ds_read_b128 v[188:191], v162 offset:21504
	ds_read_b128 v[192:195], v162 offset:22528
	ds_read_b128 v[200:203], v162 offset:23552
	buffer_load_dwordx4 v158, s[16:19], s60 offen lds
	s_mov_b32 m0, s93
	s_add_i32 s63, s60, 0x40000
	buffer_load_dwordx4 v160, s[16:19], s60 offen lds
	s_mov_b32 m0, s94
	s_nop 0
	buffer_load_dwordx4 v158, s[16:19], s63 offen lds
	s_mov_b32 m0, s95
	s_nop 0
	buffer_load_dwordx4 v160, s[16:19], s63 offen lds
	s_waitcnt vmcnt(6)
	s_waitcnt lgkmcnt(0)
	s_setprio 1
	s_barrier
	v_mfma_f32_16x16x32_bf16 v[62:65], v[130:133], v[168:171], v[62:65]
	v_mfma_f32_16x16x32_bf16 v[58:61], v[138:141], v[168:171], v[58:61]
	v_mfma_f32_16x16x32_bf16 v[46:49], v[130:133], v[176:179], v[46:49]
	v_mfma_f32_16x16x32_bf16 v[42:45], v[138:141], v[176:179], v[42:45]
	v_mfma_f32_16x16x32_bf16 v[30:33], v[130:133], v[184:187], v[30:33]
	v_mfma_f32_16x16x32_bf16 v[26:29], v[138:141], v[184:187], v[26:29]
	v_mfma_f32_16x16x32_bf16 v[14:17], v[130:133], v[192:195], v[14:17]
	v_mfma_f32_16x16x32_bf16 v[10:13], v[138:141], v[192:195], v[10:13]
	v_mfma_f32_16x16x32_bf16 v[62:65], v[134:137], v[172:175], v[62:65]
	v_mfma_f32_16x16x32_bf16 v[58:61], v[142:145], v[172:175], v[58:61]
	v_mfma_f32_16x16x32_bf16 v[46:49], v[134:137], v[180:183], v[46:49]
	v_mfma_f32_16x16x32_bf16 v[42:45], v[142:145], v[180:183], v[42:45]
	v_mfma_f32_16x16x32_bf16 v[30:33], v[134:137], v[188:191], v[30:33]
	v_mfma_f32_16x16x32_bf16 v[26:29], v[142:145], v[188:191], v[26:29]
	v_mfma_f32_16x16x32_bf16 v[14:17], v[134:137], v[200:203], v[14:17]
	v_mfma_f32_16x16x32_bf16 v[10:13], v[142:145], v[200:203], v[10:13]
	v_mfma_f32_16x16x32_bf16 v[54:57], v[146:149], v[168:171], v[54:57]
	v_mfma_f32_16x16x32_bf16 v[50:53], v[154:157], v[168:171], v[50:53]
	v_mfma_f32_16x16x32_bf16 v[38:41], v[146:149], v[176:179], v[38:41]
	v_mfma_f32_16x16x32_bf16 v[34:37], v[154:157], v[176:179], v[34:37]
	v_mfma_f32_16x16x32_bf16 v[22:25], v[146:149], v[184:187], v[22:25]
	v_mfma_f32_16x16x32_bf16 v[18:21], v[154:157], v[184:187], v[18:21]
	v_mfma_f32_16x16x32_bf16 v[6:9], v[146:149], v[192:195], v[6:9]
	v_mfma_f32_16x16x32_bf16 v[2:5], v[154:157], v[192:195], v[2:5]
	v_mfma_f32_16x16x32_bf16 v[54:57], v[150:153], v[172:175], v[54:57]
	v_mfma_f32_16x16x32_bf16 v[50:53], v[164:167], v[172:175], v[50:53]
	v_mfma_f32_16x16x32_bf16 v[38:41], v[150:153], v[180:183], v[38:41]
	v_mfma_f32_16x16x32_bf16 v[34:37], v[164:167], v[180:183], v[34:37]
	v_mfma_f32_16x16x32_bf16 v[22:25], v[150:153], v[188:191], v[22:25]
	v_mfma_f32_16x16x32_bf16 v[18:21], v[164:167], v[188:191], v[18:21]
	v_mfma_f32_16x16x32_bf16 v[6:9], v[150:153], v[200:203], v[6:9]
	v_mfma_f32_16x16x32_bf16 v[2:5], v[164:167], v[200:203], v[2:5]
	s_barrier
; #define PG8_WAIT_V(n) asm volatile("s_waitcnt vmcnt(" #n ")" ::: "memory")
; template <class Epi, bool ALIGN_EPI, bool SP2, class Hook>
; __device__ __forceinline__ void gemm_phase(LAS unsigned char* lds, const Gemm g, const StaticOrder& S, const Epi& E, Acc& acc, const bool fresh, const Hook& H, const int wave_id) {
;     ...
;         for (int t = t0; t < nt; t += 2) {
;             const bool last = (t == nt - 2);
;             const Src a1 = cA + (size_t)(t + 1) * kstep;
;             const Src a2 = last ? nA : cA + (size_t)(t + 2) * kstep, b2 = last ? nB : cB + (size_t)(t + 2) * kstep;
;             const Src a3 = a2 + kstep, b3 = b2 + kstep;
;             if (last && has_next) H(nxt);
;             if constexpr (SP2) {
;             PG8_TRIP_SP2(PG8_WAIT_V(8));
	s_setprio 0
	s_mov_b32 m0, s44
	s_nop 0
	buffer_load_dwordx4 v0, s[20:23], s62 offen lds
	s_mov_b32 m0, s36
	s_nop 0
	buffer_load_dwordx4 v159, s[20:23], s62 offen lds
	v_add_u32_e32 v142, 0x18000, v161
	v_add_u32_e32 v163, 0x1c000, v161
	ds_read_b128 v[130:133], v142
	ds_read_b128 v[134:137], v142 offset:1024
	ds_read_b128 v[138:141], v142 offset:2048
	ds_read_b128 v[142:145], v142 offset:3072
	ds_read_b128 v[146:149], v163
	ds_read_b128 v[150:153], v163 offset:1024
	ds_read_b128 v[154:157], v163 offset:2048
	ds_read_b128 v[164:167], v163 offset:3072
	s_add_i32 s62, s62, 0x40000
	s_mov_b32 m0, s37
	ds_read_b128 v[168:171], v162 offset:32768
	ds_read_b128 v[172:175], v162 offset:33792
	ds_read_b128 v[176:179], v162 offset:34816
	ds_read_b128 v[180:183], v162 offset:35840
	ds_read_b128 v[184:187], v162 offset:36864
	ds_read_b128 v[188:191], v162 offset:37888
	ds_read_b128 v[192:195], v162 offset:38912
	ds_read_b128 v[200:203], v162 offset:39936
	buffer_load_dwordx4 v0, s[20:23], s62 offen lds
	s_mov_b32 m0, s38
	s_nop 0
	buffer_load_dwordx4 v159, s[20:23], s62 offen lds
	s_waitcnt vmcnt(8)
	s_waitcnt lgkmcnt(0)
	s_setprio 1
	s_barrier
	v_mfma_f32_16x16x32_bf16 v[126:129], v[130:133], v[168:171], v[126:129]
	v_mfma_f32_16x16x32_bf16 v[122:125], v[138:141], v[168:171], v[122:125]
	v_mfma_f32_16x16x32_bf16 v[110:113], v[130:133], v[176:179], v[110:113]
	v_mfma_f32_16x16x32_bf16 v[106:109], v[138:141], v[176:179], v[106:109]
	v_mfma_f32_16x16x32_bf16 v[94:97], v[130:133], v[184:187], v[94:97]
	v_mfma_f32_16x16x32_bf16 v[90:93], v[138:141], v[184:187], v[90:93]
	v_mfma_f32_16x16x32_bf16 v[78:81], v[130:133], v[192:195], v[78:81]
	v_mfma_f32_16x16x32_bf16 v[74:77], v[138:141], v[192:195], v[74:77]
	v_mfma_f32_16x16x32_bf16 v[126:129], v[134:137], v[172:175], v[126:129]
	v_mfma_f32_16x16x32_bf16 v[122:125], v[142:145], v[172:175], v[122:125]
	v_mfma_f32_16x16x32_bf16 v[110:113], v[134:137], v[180:183], v[110:113]
	v_mfma_f32_16x16x32_bf16 v[106:109], v[142:145], v[180:183], v[106:109]
	v_mfma_f32_16x16x32_bf16 v[94:97], v[134:137], v[188:191], v[94:97]
	v_mfma_f32_16x16x32_bf16 v[90:93], v[142:145], v[188:191], v[90:93]
	v_mfma_f32_16x16x32_bf16 v[78:81], v[134:137], v[200:203], v[78:81]
	v_mfma_f32_16x16x32_bf16 v[74:77], v[142:145], v[200:203], v[74:77]
	v_mfma_f32_16x16x32_bf16 v[118:121], v[146:149], v[168:171], v[118:121]
	v_mfma_f32_16x16x32_bf16 v[114:117], v[154:157], v[168:171], v[114:117]
	v_mfma_f32_16x16x32_bf16 v[102:105], v[146:149], v[176:179], v[102:105]
	v_mfma_f32_16x16x32_bf16 v[98:101], v[154:157], v[176:179], v[98:101]
	v_mfma_f32_16x16x32_bf16 v[86:89], v[146:149], v[184:187], v[86:89]
	v_mfma_f32_16x16x32_bf16 v[82:85], v[154:157], v[184:187], v[82:85]
	v_mfma_f32_16x16x32_bf16 v[70:73], v[146:149], v[192:195], v[70:73]
	v_mfma_f32_16x16x32_bf16 v[66:69], v[154:157], v[192:195], v[66:69]
	v_mfma_f32_16x16x32_bf16 v[118:121], v[150:153], v[172:175], v[118:121]
	v_mfma_f32_16x16x32_bf16 v[114:117], v[164:167], v[172:175], v[114:117]
	v_mfma_f32_16x16x32_bf16 v[102:105], v[150:153], v[180:183], v[102:105]
	v_mfma_f32_16x16x32_bf16 v[98:101], v[164:167], v[180:183], v[98:101]
	v_mfma_f32_16x16x32_bf16 v[86:89], v[150:153], v[188:191], v[86:89]
	v_mfma_f32_16x16x32_bf16 v[82:85], v[164:167], v[188:191], v[82:85]
	v_mfma_f32_16x16x32_bf16 v[70:73], v[150:153], v[200:203], v[70:73]
	v_mfma_f32_16x16x32_bf16 v[66:69], v[164:167], v[200:203], v[66:69]
	s_barrier
	s_setprio 0
	s_mov_b32 m0, s39
	s_or_b32 s62, s60, 0x80
	ds_read_b128 v[168:171], v162 offset:49152
	ds_read_b128 v[172:175], v162 offset:50176
	ds_read_b128 v[176:179], v162 offset:51200
	ds_read_b128 v[180:183], v162 offset:52224
	ds_read_b128 v[184:187], v162 offset:53248
	ds_read_b128 v[188:191], v162 offset:54272
	ds_read_b128 v[192:195], v162 offset:55296
	ds_read_b128 v[200:203], v162 offset:56320
	buffer_load_dwordx4 v158, s[16:19], s62 offen lds
	s_mov_b32 m0, s40
	s_add_i32 s60, s60, 0x40080
	buffer_load_dwordx4 v160, s[16:19], s62 offen lds
	s_mov_b32 m0, s43
	s_nop 0
	buffer_load_dwordx4 v158, s[16:19], s60 offen lds
	s_mov_b32 m0, s42
	s_nop 0
	buffer_load_dwordx4 v160, s[16:19], s60 offen lds
	s_waitcnt vmcnt(6)
	s_waitcnt lgkmcnt(0)
	s_setprio 1
	s_barrier
	v_mfma_f32_16x16x32_bf16 v[62:65], v[130:133], v[168:171], v[62:65]
	v_mfma_f32_16x16x32_bf16 v[58:61], v[138:141], v[168:171], v[58:61]
	v_mfma_f32_16x16x32_bf16 v[46:49], v[130:133], v[176:179], v[46:49]
	v_mfma_f32_16x16x32_bf16 v[42:45], v[138:141], v[176:179], v[42:45]
	v_mfma_f32_16x16x32_bf16 v[30:33], v[130:133], v[184:187], v[30:33]
	v_mfma_f32_16x16x32_bf16 v[26:29], v[138:141], v[184:187], v[26:29]
	v_mfma_f32_16x16x32_bf16 v[14:17], v[130:133], v[192:195], v[14:17]
	v_mfma_f32_16x16x32_bf16 v[10:13], v[138:141], v[192:195], v[10:13]
	v_mfma_f32_16x16x32_bf16 v[62:65], v[134:137], v[172:175], v[62:65]
	v_mfma_f32_16x16x32_bf16 v[58:61], v[142:145], v[172:175], v[58:61]
	v_mfma_f32_16x16x32_bf16 v[46:49], v[134:137], v[180:183], v[46:49]
	v_mfma_f32_16x16x32_bf16 v[42:45], v[142:145], v[180:183], v[42:45]
	v_mfma_f32_16x16x32_bf16 v[30:33], v[134:137], v[188:191], v[30:33]
	v_mfma_f32_16x16x32_bf16 v[26:29], v[142:145], v[188:191], v[26:29]
	v_mfma_f32_16x16x32_bf16 v[14:17], v[134:137], v[200:203], v[14:17]
	v_mfma_f32_16x16x32_bf16 v[10:13], v[142:145], v[200:203], v[10:13]
	v_mfma_f32_16x16x32_bf16 v[54:57], v[146:149], v[168:171], v[54:57]
	v_mfma_f32_16x16x32_bf16 v[50:53], v[154:157], v[168:171], v[50:53]
	v_mfma_f32_16x16x32_bf16 v[38:41], v[146:149], v[176:179], v[38:41]
	v_mfma_f32_16x16x32_bf16 v[34:37], v[154:157], v[176:179], v[34:37]
	v_mfma_f32_16x16x32_bf16 v[22:25], v[146:149], v[184:187], v[22:25]
	v_mfma_f32_16x16x32_bf16 v[18:21], v[154:157], v[184:187], v[18:21]
	v_mfma_f32_16x16x32_bf16 v[6:9], v[146:149], v[192:195], v[6:9]
	v_mfma_f32_16x16x32_bf16 v[2:5], v[154:157], v[192:195], v[2:5]
	v_mfma_f32_16x16x32_bf16 v[54:57], v[150:153], v[172:175], v[54:57]
	v_mfma_f32_16x16x32_bf16 v[50:53], v[164:167], v[172:175], v[50:53]
	v_mfma_f32_16x16x32_bf16 v[38:41], v[150:153], v[180:183], v[38:41]
	v_mfma_f32_16x16x32_bf16 v[34:37], v[164:167], v[180:183], v[34:37]
	v_mfma_f32_16x16x32_bf16 v[22:25], v[150:153], v[188:191], v[22:25]
	v_mfma_f32_16x16x32_bf16 v[18:21], v[164:167], v[188:191], v[18:21]
	v_mfma_f32_16x16x32_bf16 v[6:9], v[150:153], v[200:203], v[6:9]
	v_mfma_f32_16x16x32_bf16 v[2:5], v[164:167], v[200:203], v[2:5]
	s_barrier
	s_setprio 0
	s_add_i32 s59, s59, 2
	s_addk_i32 s2, 0x100
	s_addk_i32 s3, 0x100
	s_cmp_gt_u32 s59, 13
	s_cbranch_scc0 .LBB0_1235
	s_mov_b32 m0, s41
	s_nop 0
	buffer_load_dwordx4 v0, s[20:23], s61 offen lds
	s_mov_b32 m0, s33
	s_nop 0
	buffer_load_dwordx4 v159, s[20:23], s61 offen lds
	v_readlane_b32 s2, v251, 45
	v_readlane_b32 s3, v251, 46
	s_and_b64 vcc, exec, s[2:3]
	s_cbranch_vccz .LBB0_1238
	s_barrier

; #define PG8_WAIT_V(n) asm volatile("s_waitcnt vmcnt(" #n ")" ::: "memory")
; template <class Epi, bool ALIGN_EPI, bool SP2, class Hook>
; __device__ __forceinline__ void gemm_phase(LAS unsigned char* lds, const Gemm g, const StaticOrder& S, const Epi& E, Acc& acc, const bool fresh, const Hook& H, const int wave_id) {
;     ...
;         if constexpr (SP2 && Epi::NSTORE > 0) {
;             const Src a1 = cA + kstep, a2 = cA + 2 * kstep, b2 = cB + 2 * kstep, a3 = a2 + kstep, b3 = b2 + kstep;
;             if constexpr (Epi::NSTORE == 16) PG8_TRIP_SP2(PG8_WAIT_V(24)); else PG8_TRIP_SP2(PG8_WAIT_V(16));
;             t0 = 2;
.LBB0_1452:
	ds_read_b128 v[2:5], v138
	ds_read_b128 v[6:9], v138 offset:1024
	ds_read_b128 v[10:13], v138 offset:2048
	ds_read_b128 v[14:17], v138 offset:3072
	ds_read_b128 v[18:21], v139
	ds_read_b128 v[22:25], v139 offset:1024
	ds_read_b128 v[26:29], v139 offset:2048
	ds_read_b128 v[30:33], v139 offset:3072
	s_or_b32 s3, s50, 0x100
	s_or_b32 s2, s50, 0x180
	s_or_b32 s12, s51, 0x100
	s_or_b32 s13, s50, 0x40080
	s_mov_b32 m0, s45
	ds_read_b128 v[34:37], v137
	ds_read_b128 v[38:41], v137 offset:1024
	ds_read_b128 v[42:45], v137 offset:2048
	ds_read_b128 v[46:49], v137 offset:3072
	ds_read_b128 v[50:53], v137 offset:4096
	ds_read_b128 v[54:57], v137 offset:5120
	ds_read_b128 v[58:61], v137 offset:6144
	ds_read_b128 v[62:65], v137 offset:7168
	buffer_load_dwordx4 v132, s[4:7], s13 offen lds
	s_mov_b32 m0, s46
	s_nop 0
	buffer_load_dwordx4 v134, s[4:7], s13 offen lds
	s_waitcnt vmcnt(16)
	s_waitcnt lgkmcnt(0)
	s_setprio 1
	s_barrier
	v_mfma_f32_16x16x32_bf16 v[90:93], v[2:5], v[58:61], 0
	v_mfma_f32_16x16x32_bf16 v[66:69], v[2:5], v[34:37], 0
	v_mfma_f32_16x16x32_bf16 v[70:73], v[10:13], v[34:37], 0
	v_mfma_f32_16x16x32_bf16 v[74:77], v[2:5], v[42:45], 0
	v_mfma_f32_16x16x32_bf16 v[78:81], v[10:13], v[42:45], 0
	v_mfma_f32_16x16x32_bf16 v[82:85], v[2:5], v[50:53], 0
	v_mfma_f32_16x16x32_bf16 v[86:89], v[10:13], v[50:53], 0
	v_mfma_f32_16x16x32_bf16 v[96:99], v[6:9], v[62:65], v[90:93]
	v_mfma_f32_16x16x32_bf16 v[90:93], v[10:13], v[58:61], 0
	v_mfma_f32_16x16x32_bf16 v[66:69], v[6:9], v[38:41], v[66:69]
	v_mfma_f32_16x16x32_bf16 v[70:73], v[14:17], v[38:41], v[70:73]
	v_mfma_f32_16x16x32_bf16 v[74:77], v[6:9], v[46:49], v[74:77]
	v_mfma_f32_16x16x32_bf16 v[78:81], v[14:17], v[46:49], v[78:81]
	v_mfma_f32_16x16x32_bf16 v[82:85], v[6:9], v[54:57], v[82:85]
	v_mfma_f32_16x16x32_bf16 v[86:89], v[14:17], v[54:57], v[86:89]
	v_mfma_f32_16x16x32_bf16 v[104:107], v[14:17], v[62:65], v[90:93]
	v_mfma_f32_16x16x32_bf16 v[90:93], v[18:21], v[34:37], 0
	v_mfma_f32_16x16x32_bf16 v[34:37], v[26:29], v[34:37], 0
	v_mfma_f32_16x16x32_bf16 v[112:115], v[22:25], v[38:41], v[90:93]
	v_mfma_f32_16x16x32_bf16 v[34:37], v[30:33], v[38:41], v[34:37]
	v_mfma_f32_16x16x32_bf16 v[38:41], v[18:21], v[42:45], 0
	v_mfma_f32_16x16x32_bf16 v[42:45], v[26:29], v[42:45], 0
	v_mfma_f32_16x16x32_bf16 v[38:41], v[22:25], v[46:49], v[38:41]
	v_mfma_f32_16x16x32_bf16 v[42:45], v[30:33], v[46:49], v[42:45]
	v_mfma_f32_16x16x32_bf16 v[46:49], v[18:21], v[50:53], 0
	v_mfma_f32_16x16x32_bf16 v[50:53], v[26:29], v[50:53], 0
	v_mfma_f32_16x16x32_bf16 v[46:49], v[22:25], v[54:57], v[46:49]
	v_mfma_f32_16x16x32_bf16 v[50:53], v[30:33], v[54:57], v[50:53]
	v_mfma_f32_16x16x32_bf16 v[54:57], v[18:21], v[58:61], 0
	v_mfma_f32_16x16x32_bf16 v[58:61], v[26:29], v[58:61], 0
	v_mfma_f32_16x16x32_bf16 v[54:57], v[22:25], v[62:65], v[54:57]
	v_mfma_f32_16x16x32_bf16 v[58:61], v[30:33], v[62:65], v[58:61]
	s_barrier
	s_setprio 0
	s_mov_b32 m0, s92
	ds_read_b128 v[62:65], v137 offset:16384
	ds_read_b128 v[90:93], v137 offset:17408
	ds_read_b128 v[100:103], v137 offset:18432
	ds_read_b128 v[108:111], v137 offset:19456
	ds_read_b128 v[116:119], v137 offset:20480
	ds_read_b128 v[120:123], v137 offset:21504
	ds_read_b128 v[124:127], v137 offset:22528
	ds_read_b128 v[128:131], v137 offset:23552
	buffer_load_dwordx4 v133, s[8:11], s12 offen lds
	s_mov_b32 m0, s93
	s_nop 0
	buffer_load_dwordx4 v135, s[8:11], s12 offen lds
	s_or_b32 s12, s51, 0x40100
	s_mov_b32 m0, s94
	s_nop 0
	buffer_load_dwordx4 v133, s[8:11], s12 offen lds
	s_mov_b32 m0, s95
	s_nop 0
	buffer_load_dwordx4 v135, s[8:11], s12 offen lds
	s_waitcnt vmcnt(14)
	s_waitcnt lgkmcnt(0)
	s_setprio 1
	s_barrier
	v_mfma_f32_16x16x32_bf16 v[142:145], v[2:5], v[62:65], 0
	v_mfma_f32_16x16x32_bf16 v[150:153], v[2:5], v[100:103], 0
	v_mfma_f32_16x16x32_bf16 v[158:161], v[2:5], v[116:119], 0
	v_mfma_f32_16x16x32_bf16 v[2:5], v[2:5], v[124:127], 0
	v_mfma_f32_16x16x32_bf16 v[142:145], v[6:9], v[90:93], v[142:145]
	v_mfma_f32_16x16x32_bf16 v[150:153], v[6:9], v[108:111], v[150:153]
	v_mfma_f32_16x16x32_bf16 v[158:161], v[6:9], v[120:123], v[158:161]
	v_mfma_f32_16x16x32_bf16 v[2:5], v[6:9], v[128:131], v[2:5]
	v_mfma_f32_16x16x32_bf16 v[6:9], v[10:13], v[124:127], 0
	v_mfma_f32_16x16x32_bf16 v[146:149], v[10:13], v[62:65], 0
	v_mfma_f32_16x16x32_bf16 v[154:157], v[10:13], v[100:103], 0
	v_mfma_f32_16x16x32_bf16 v[162:165], v[10:13], v[116:119], 0
	v_mfma_f32_16x16x32_bf16 v[6:9], v[14:17], v[128:131], v[6:9]
	v_mfma_f32_16x16x32_bf16 v[146:149], v[14:17], v[90:93], v[146:149]
	v_mfma_f32_16x16x32_bf16 v[154:157], v[14:17], v[108:111], v[154:157]
	v_mfma_f32_16x16x32_bf16 v[162:165], v[14:17], v[120:123], v[162:165]
	v_mfma_f32_16x16x32_bf16 v[10:13], v[18:21], v[62:65], 0
	v_mfma_f32_16x16x32_bf16 v[166:169], v[22:25], v[90:93], v[10:13]
	v_mfma_f32_16x16x32_bf16 v[10:13], v[26:29], v[62:65], 0
	v_mfma_f32_16x16x32_bf16 v[170:173], v[30:33], v[90:93], v[10:13]
	v_mfma_f32_16x16x32_bf16 v[10:13], v[18:21], v[100:103], 0
	v_mfma_f32_16x16x32_bf16 v[174:177], v[22:25], v[108:111], v[10:13]
	v_mfma_f32_16x16x32_bf16 v[10:13], v[26:29], v[100:103], 0
	v_mfma_f32_16x16x32_bf16 v[178:181], v[30:33], v[108:111], v[10:13]
	v_mfma_f32_16x16x32_bf16 v[10:13], v[18:21], v[116:119], 0
	v_mfma_f32_16x16x32_bf16 v[182:185], v[22:25], v[120:123], v[10:13]
	v_mfma_f32_16x16x32_bf16 v[10:13], v[26:29], v[116:119], 0
	v_mfma_f32_16x16x32_bf16 v[186:189], v[30:33], v[120:123], v[10:13]
	v_mfma_f32_16x16x32_bf16 v[10:13], v[18:21], v[124:127], 0
	v_mfma_f32_16x16x32_bf16 v[16:19], v[22:25], v[128:131], v[10:13]
	v_mfma_f32_16x16x32_bf16 v[10:13], v[26:29], v[124:127], 0
	v_mfma_f32_16x16x32_bf16 v[190:193], v[30:33], v[128:131], v[10:13]
	s_barrier
; #define PG8_WAIT_V(n) asm volatile("s_waitcnt vmcnt(" #n ")" ::: "memory")
; template <class Epi, bool ALIGN_EPI, bool SP2, class Hook>
; __device__ __forceinline__ void gemm_phase(LAS unsigned char* lds, const Gemm g, const StaticOrder& S, const Epi& E, Acc& acc, const bool fresh, const Hook& H, const int wave_id) {
;     ...
;         if constexpr (SP2 && Epi::NSTORE > 0) {
;             const Src a1 = cA + kstep, a2 = cA + 2 * kstep, b2 = cB + 2 * kstep, a3 = a2 + kstep, b3 = b2 + kstep;
;             if constexpr (Epi::NSTORE == 16) PG8_TRIP_SP2(PG8_WAIT_V(24)); else PG8_TRIP_SP2(PG8_WAIT_V(16));
;             t0 = 2;
	s_setprio 0
	s_mov_b32 m0, s44
	s_nop 0
	buffer_load_dwordx4 v132, s[4:7], s3 offen lds
	s_mov_b32 m0, s36
	s_nop 0
	buffer_load_dwordx4 v134, s[4:7], s3 offen lds
	s_nop 4
	ds_read_b128 v[10:13], v140
	ds_read_b128 v[24:27], v140 offset:1024
	ds_read_b128 v[194:197], v140 offset:2048
	ds_read_b128 v[200:203], v140 offset:3072
	ds_read_b128 v[204:207], v141
	ds_read_b128 v[208:211], v141 offset:1024
	ds_read_b128 v[212:215], v141 offset:2048
	ds_read_b128 v[138:141], v141 offset:3072
	s_or_b32 s3, s50, 0x40100
	s_mov_b32 m0, s37
	ds_read_b128 v[20:23], v137 offset:32768
	ds_read_b128 v[28:31], v137 offset:33792
	ds_read_b128 v[216:219], v137 offset:34816
	ds_read_b128 v[220:223], v137 offset:35840
	ds_read_b128 v[228:231], v137 offset:36864
	ds_read_b128 v[232:235], v137 offset:37888
	ds_read_b128 v[236:239], v137 offset:38912
	ds_read_b128 v[240:243], v137 offset:39936
	buffer_load_dwordx4 v132, s[4:7], s3 offen lds
	s_mov_b32 m0, s38
	s_nop 0
	buffer_load_dwordx4 v134, s[4:7], s3 offen lds
	s_waitcnt vmcnt(8)
	s_waitcnt lgkmcnt(0)
	s_setprio 1
	s_barrier
	v_mfma_f32_16x16x32_bf16 v[62:65], v[10:13], v[20:23], v[66:69]
	v_mfma_f32_16x16x32_bf16 v[124:127], v[24:27], v[28:31], v[62:65]
	v_mfma_f32_16x16x32_bf16 v[62:65], v[194:197], v[20:23], v[70:73]
	v_mfma_f32_16x16x32_bf16 v[116:119], v[200:203], v[28:31], v[62:65]
	v_mfma_f32_16x16x32_bf16 v[62:65], v[10:13], v[216:219], v[74:77]
	v_mfma_f32_16x16x32_bf16 v[108:111], v[24:27], v[220:223], v[62:65]
	v_mfma_f32_16x16x32_bf16 v[62:65], v[194:197], v[216:219], v[78:81]
	v_mfma_f32_16x16x32_bf16 v[100:103], v[200:203], v[220:223], v[62:65]
	v_mfma_f32_16x16x32_bf16 v[62:65], v[10:13], v[228:231], v[82:85]
	v_mfma_f32_16x16x32_bf16 v[92:95], v[24:27], v[232:235], v[62:65]
	v_mfma_f32_16x16x32_bf16 v[62:65], v[194:197], v[228:231], v[86:89]
	v_mfma_f32_16x16x32_bf16 v[84:87], v[200:203], v[232:235], v[62:65]
	v_mfma_f32_16x16x32_bf16 v[62:65], v[10:13], v[236:239], v[96:99]
	v_mfma_f32_16x16x32_bf16 v[76:79], v[24:27], v[240:243], v[62:65]
	v_mfma_f32_16x16x32_bf16 v[62:65], v[194:197], v[236:239], v[104:107]
	v_mfma_f32_16x16x32_bf16 v[64:67], v[200:203], v[240:243], v[62:65]
	v_mfma_f32_16x16x32_bf16 v[68:71], v[204:207], v[20:23], v[112:115]
	v_mfma_f32_16x16x32_bf16 v[20:23], v[212:215], v[20:23], v[34:37]
	v_mfma_f32_16x16x32_bf16 v[120:123], v[138:141], v[28:31], v[20:23]
	v_mfma_f32_16x16x32_bf16 v[20:23], v[204:207], v[216:219], v[38:41]
	v_mfma_f32_16x16x32_bf16 v[112:115], v[208:211], v[220:223], v[20:23]
	v_mfma_f32_16x16x32_bf16 v[20:23], v[212:215], v[216:219], v[42:45]
	v_mfma_f32_16x16x32_bf16 v[104:107], v[138:141], v[220:223], v[20:23]
	v_mfma_f32_16x16x32_bf16 v[20:23], v[204:207], v[228:231], v[46:49]
	v_mfma_f32_16x16x32_bf16 v[96:99], v[208:211], v[232:235], v[20:23]
	v_mfma_f32_16x16x32_bf16 v[20:23], v[212:215], v[228:231], v[50:53]
	v_mfma_f32_16x16x32_bf16 v[88:91], v[138:141], v[232:235], v[20:23]
	v_mfma_f32_16x16x32_bf16 v[20:23], v[204:207], v[236:239], v[54:57]
	v_mfma_f32_16x16x32_bf16 v[80:83], v[208:211], v[240:243], v[20:23]
	v_mfma_f32_16x16x32_bf16 v[20:23], v[212:215], v[236:239], v[58:61]
	v_mfma_f32_16x16x32_bf16 v[128:131], v[208:211], v[28:31], v[68:71]
	v_mfma_f32_16x16x32_bf16 v[68:71], v[138:141], v[240:243], v[20:23]
	s_barrier
	s_setprio 0
	s_mov_b32 m0, s39
	s_or_b32 s3, s51, 0x180
	ds_read_b128 v[32:35], v137 offset:49152
	ds_read_b128 v[40:43], v137 offset:50176
	ds_read_b128 v[216:219], v137 offset:51200
	ds_read_b128 v[220:223], v137 offset:52224
	ds_read_b128 v[228:231], v137 offset:53248
	ds_read_b128 v[232:235], v137 offset:54272
	ds_read_b128 v[236:239], v137 offset:55296
	ds_read_b128 v[240:243], v137 offset:56320
	buffer_load_dwordx4 v133, s[8:11], s3 offen lds
	s_mov_b32 m0, s40
	s_nop 0
	buffer_load_dwordx4 v135, s[8:11], s3 offen lds
	s_or_b32 s3, s51, 0x40180
	s_mov_b32 m0, s43
	s_nop 0
	buffer_load_dwordx4 v133, s[8:11], s3 offen lds
	s_mov_b32 m0, s42
	s_nop 0
	buffer_load_dwordx4 v135, s[8:11], s3 offen lds
	s_waitcnt vmcnt(6)
	s_waitcnt lgkmcnt(0)
	s_setprio 1
	s_barrier
	v_mfma_f32_16x16x32_bf16 v[20:23], v[10:13], v[32:35], v[142:145]
	v_mfma_f32_16x16x32_bf16 v[60:63], v[24:27], v[40:43], v[20:23]
	v_mfma_f32_16x16x32_bf16 v[20:23], v[194:197], v[32:35], v[146:149]
	v_mfma_f32_16x16x32_bf16 v[52:55], v[200:203], v[40:43], v[20:23]
	v_mfma_f32_16x16x32_bf16 v[20:23], v[10:13], v[216:219], v[150:153]
	v_mfma_f32_16x16x32_bf16 v[44:47], v[24:27], v[220:223], v[20:23]
	v_mfma_f32_16x16x32_bf16 v[20:23], v[194:197], v[216:219], v[154:157]
	v_mfma_f32_16x16x32_bf16 v[36:39], v[200:203], v[220:223], v[20:23]
	v_mfma_f32_16x16x32_bf16 v[20:23], v[10:13], v[228:231], v[158:161]
	v_mfma_f32_16x16x32_bf16 v[2:5], v[10:13], v[236:239], v[2:5]
	v_mfma_f32_16x16x32_bf16 v[28:31], v[24:27], v[232:235], v[20:23]
	v_mfma_f32_16x16x32_bf16 v[20:23], v[194:197], v[228:231], v[162:165]
	v_mfma_f32_16x16x32_bf16 v[12:15], v[24:27], v[240:243], v[2:5]
	v_mfma_f32_16x16x32_bf16 v[2:5], v[194:197], v[236:239], v[6:9]
	v_mfma_f32_16x16x32_bf16 v[20:23], v[200:203], v[232:235], v[20:23]
	v_mfma_f32_16x16x32_bf16 v[4:7], v[200:203], v[240:243], v[2:5]
	v_mfma_f32_16x16x32_bf16 v[8:11], v[204:207], v[32:35], v[166:169]
	v_mfma_f32_16x16x32_bf16 v[72:75], v[208:211], v[40:43], v[8:11]
	v_mfma_f32_16x16x32_bf16 v[8:11], v[212:215], v[32:35], v[170:173]
	v_mfma_f32_16x16x32_bf16 v[56:59], v[138:141], v[40:43], v[8:11]
	v_mfma_f32_16x16x32_bf16 v[8:11], v[204:207], v[216:219], v[174:177]
	v_mfma_f32_16x16x32_bf16 v[48:51], v[208:211], v[220:223], v[8:11]
	v_mfma_f32_16x16x32_bf16 v[8:11], v[212:215], v[216:219], v[178:181]
	v_mfma_f32_16x16x32_bf16 v[40:43], v[138:141], v[220:223], v[8:11]
	v_mfma_f32_16x16x32_bf16 v[8:11], v[204:207], v[228:231], v[182:185]
	v_mfma_f32_16x16x32_bf16 v[32:35], v[208:211], v[232:235], v[8:11]
	v_mfma_f32_16x16x32_bf16 v[8:11], v[212:215], v[228:231], v[186:189]
	v_mfma_f32_16x16x32_bf16 v[24:27], v[138:141], v[232:235], v[8:11]
	v_mfma_f32_16x16x32_bf16 v[8:11], v[204:207], v[236:239], v[16:19]
	v_mfma_f32_16x16x32_bf16 v[16:19], v[208:211], v[240:243], v[8:11]
	v_mfma_f32_16x16x32_bf16 v[8:11], v[212:215], v[236:239], v[190:193]
	v_mfma_f32_16x16x32_bf16 v[8:11], v[138:141], v[240:243], v[8:11]
	s_barrier
	s_setprio 0
	s_mov_b64 s[2:3], 0
	v_mov_b64_e32 v[234:235], v[226:227]
	v_mov_b32_e32 v226, v0
	v_mov_b64_e32 v[236:237], v[198:199]
	v_mov_b32_e32 v198, v225

; #define PG8_WAIT_V(n) asm volatile("s_waitcnt vmcnt(" #n ")" ::: "memory")
; template <class Epi, bool ALIGN_EPI, bool SP2, class Hook>
; __device__ __forceinline__ void gemm_phase(LAS unsigned char* lds, const Gemm g, const StaticOrder& S, const Epi& E, Acc& acc, const bool fresh, const Hook& H, const int wave_id) {
;     ...
;         for (int t = t0; t < nt; t += 2) {
;             const bool last = (t == nt - 2);
;             const Src a1 = cA + (size_t)(t + 1) * kstep;
;             const Src a2 = last ? nA : cA + (size_t)(t + 2) * kstep, b2 = last ? nB : cB + (size_t)(t + 2) * kstep;
;             const Src a3 = a2 + kstep, b3 = b2 + kstep;
;             if (last && has_next) H(nxt);
;             if constexpr (SP2) {
;             PG8_TRIP_SP2(PG8_WAIT_V(8));
.LBB0_1461:
	s_add_i32 s100, s55, 0xfffc0000
	v_add_u32_e32 v138, 0x10000, v136
	v_add_u32_e32 v139, 0x14000, v136
	ds_read_b128 v[140:143], v138
	ds_read_b128 v[144:147], v138 offset:1024
	ds_read_b128 v[148:151], v138 offset:2048
	ds_read_b128 v[152:155], v138 offset:3072
	ds_read_b128 v[156:159], v139
	ds_read_b128 v[160:163], v139 offset:1024
	ds_read_b128 v[164:167], v139 offset:2048
	ds_read_b128 v[168:171], v139 offset:3072
	s_add_i32 s16, s55, 0xfffc0080
	s_cmp_eq_u32 s54, 12
	s_cselect_b32 s59, s50, s16
	s_cselect_b32 s17, s9, s77
	s_cselect_b32 s16, s8, s76
	s_cselect_b32 s19, s11, s29
	s_cselect_b32 s18, s10, s28
	s_cselect_b32 s57, s51, s56
	s_cselect_b32 s20, s4, s12
	s_cselect_b32 s21, s5, s13
	s_cselect_b32 s22, s6, s14
	s_cselect_b32 s23, s7, s15
	s_or_b32 s58, s59, 0x80
	s_mov_b32 m0, s41
	s_nop 0
	buffer_load_dwordx4 v132, s[12:15], s100 offen lds
	s_mov_b32 m0, s33
	s_nop 0
	buffer_load_dwordx4 v134, s[12:15], s100 offen lds
	s_mov_b32 m0, s45
	ds_read_b128 v[172:175], v137
	ds_read_b128 v[176:179], v137 offset:1024
	ds_read_b128 v[180:183], v137 offset:2048
	ds_read_b128 v[184:187], v137 offset:3072
	ds_read_b128 v[188:191], v137 offset:4096
	ds_read_b128 v[192:195], v137 offset:5120
	ds_read_b128 v[200:203], v137 offset:6144
	ds_read_b128 v[204:207], v137 offset:7168
	buffer_load_dwordx4 v132, s[12:15], s55 offen lds
	s_mov_b32 m0, s46
	s_nop 0
	buffer_load_dwordx4 v134, s[12:15], s55 offen lds
	s_waitcnt vmcnt(8)
	s_waitcnt lgkmcnt(0)
	s_setprio 1
	s_barrier
	v_mfma_f32_16x16x32_bf16 v[124:127], v[140:143], v[172:175], v[124:127]
	v_mfma_f32_16x16x32_bf16 v[116:119], v[148:151], v[172:175], v[116:119]
	v_mfma_f32_16x16x32_bf16 v[108:111], v[140:143], v[180:183], v[108:111]
	v_mfma_f32_16x16x32_bf16 v[100:103], v[148:151], v[180:183], v[100:103]
	v_mfma_f32_16x16x32_bf16 v[92:95], v[140:143], v[188:191], v[92:95]
	v_mfma_f32_16x16x32_bf16 v[84:87], v[148:151], v[188:191], v[84:87]
	v_mfma_f32_16x16x32_bf16 v[76:79], v[140:143], v[200:203], v[76:79]
	v_mfma_f32_16x16x32_bf16 v[64:67], v[148:151], v[200:203], v[64:67]
	v_mfma_f32_16x16x32_bf16 v[124:127], v[144:147], v[176:179], v[124:127]
	v_mfma_f32_16x16x32_bf16 v[116:119], v[152:155], v[176:179], v[116:119]
	v_mfma_f32_16x16x32_bf16 v[108:111], v[144:147], v[184:187], v[108:111]
	v_mfma_f32_16x16x32_bf16 v[100:103], v[152:155], v[184:187], v[100:103]
	v_mfma_f32_16x16x32_bf16 v[92:95], v[144:147], v[192:195], v[92:95]
	v_mfma_f32_16x16x32_bf16 v[84:87], v[152:155], v[192:195], v[84:87]
	v_mfma_f32_16x16x32_bf16 v[76:79], v[144:147], v[204:207], v[76:79]
	v_mfma_f32_16x16x32_bf16 v[64:67], v[152:155], v[204:207], v[64:67]
	v_mfma_f32_16x16x32_bf16 v[128:131], v[156:159], v[172:175], v[128:131]
	v_mfma_f32_16x16x32_bf16 v[120:123], v[164:167], v[172:175], v[120:123]
	v_mfma_f32_16x16x32_bf16 v[112:115], v[156:159], v[180:183], v[112:115]
	v_mfma_f32_16x16x32_bf16 v[104:107], v[164:167], v[180:183], v[104:107]
	v_mfma_f32_16x16x32_bf16 v[96:99], v[156:159], v[188:191], v[96:99]
	v_mfma_f32_16x16x32_bf16 v[88:91], v[164:167], v[188:191], v[88:91]
	v_mfma_f32_16x16x32_bf16 v[80:83], v[156:159], v[200:203], v[80:83]
	v_mfma_f32_16x16x32_bf16 v[68:71], v[164:167], v[200:203], v[68:71]
	v_mfma_f32_16x16x32_bf16 v[128:131], v[160:163], v[176:179], v[128:131]
	v_mfma_f32_16x16x32_bf16 v[120:123], v[168:171], v[176:179], v[120:123]
	v_mfma_f32_16x16x32_bf16 v[112:115], v[160:163], v[184:187], v[112:115]
	v_mfma_f32_16x16x32_bf16 v[104:107], v[168:171], v[184:187], v[104:107]
	v_mfma_f32_16x16x32_bf16 v[96:99], v[160:163], v[192:195], v[96:99]
	v_mfma_f32_16x16x32_bf16 v[88:91], v[168:171], v[192:195], v[88:91]
	v_mfma_f32_16x16x32_bf16 v[80:83], v[160:163], v[204:207], v[80:83]
	v_mfma_f32_16x16x32_bf16 v[68:71], v[168:171], v[204:207], v[68:71]
	s_barrier
	s_setprio 0
	s_mov_b32 m0, s92
	ds_read_b128 v[172:175], v137 offset:16384
	ds_read_b128 v[176:179], v137 offset:17408
	ds_read_b128 v[180:183], v137 offset:18432
	ds_read_b128 v[184:187], v137 offset:19456
	ds_read_b128 v[188:191], v137 offset:20480
	ds_read_b128 v[192:195], v137 offset:21504
	ds_read_b128 v[200:203], v137 offset:22528
	ds_read_b128 v[204:207], v137 offset:23552
	buffer_load_dwordx4 v133, s[16:19], s57 offen lds
	s_mov_b32 m0, s93
	s_add_i32 s60, s57, 0x40000
	buffer_load_dwordx4 v135, s[16:19], s57 offen lds
	s_mov_b32 m0, s94
	s_nop 0
	buffer_load_dwordx4 v133, s[16:19], s60 offen lds
	s_mov_b32 m0, s95
	s_nop 0
	buffer_load_dwordx4 v135, s[16:19], s60 offen lds
	s_waitcnt vmcnt(6)
	s_waitcnt lgkmcnt(0)
	s_setprio 1
	s_barrier
; #define PG8_WAIT_V(n) asm volatile("s_waitcnt vmcnt(" #n ")" ::: "memory")
; template <class Epi, bool ALIGN_EPI, bool SP2, class Hook>
; __device__ __forceinline__ void gemm_phase(LAS unsigned char* lds, const Gemm g, const StaticOrder& S, const Epi& E, Acc& acc, const bool fresh, const Hook& H, const int wave_id) {
;     ...
;         for (int t = t0; t < nt; t += 2) {
;             const bool last = (t == nt - 2);
;             const Src a1 = cA + (size_t)(t + 1) * kstep;
;             const Src a2 = last ? nA : cA + (size_t)(t + 2) * kstep, b2 = last ? nB : cB + (size_t)(t + 2) * kstep;
;             const Src a3 = a2 + kstep, b3 = b2 + kstep;
;             if (last && has_next) H(nxt);
;             if constexpr (SP2) {
;             PG8_TRIP_SP2(PG8_WAIT_V(8));
	v_mfma_f32_16x16x32_bf16 v[60:63], v[140:143], v[172:175], v[60:63]
	v_mfma_f32_16x16x32_bf16 v[52:55], v[148:151], v[172:175], v[52:55]
	v_mfma_f32_16x16x32_bf16 v[44:47], v[140:143], v[180:183], v[44:47]
	v_mfma_f32_16x16x32_bf16 v[36:39], v[148:151], v[180:183], v[36:39]
	v_mfma_f32_16x16x32_bf16 v[28:31], v[140:143], v[188:191], v[28:31]
	v_mfma_f32_16x16x32_bf16 v[20:23], v[148:151], v[188:191], v[20:23]
	v_mfma_f32_16x16x32_bf16 v[12:15], v[140:143], v[200:203], v[12:15]
	v_mfma_f32_16x16x32_bf16 v[2:5], v[148:151], v[200:203], v[4:7]
	v_mfma_f32_16x16x32_bf16 v[60:63], v[144:147], v[176:179], v[60:63]
	v_mfma_f32_16x16x32_bf16 v[52:55], v[152:155], v[176:179], v[52:55]
	v_mfma_f32_16x16x32_bf16 v[44:47], v[144:147], v[184:187], v[44:47]
	v_mfma_f32_16x16x32_bf16 v[36:39], v[152:155], v[184:187], v[36:39]
	v_mfma_f32_16x16x32_bf16 v[28:31], v[144:147], v[192:195], v[28:31]
	v_mfma_f32_16x16x32_bf16 v[20:23], v[152:155], v[192:195], v[20:23]
	v_mfma_f32_16x16x32_bf16 v[12:15], v[144:147], v[204:207], v[12:15]
	v_mfma_f32_16x16x32_bf16 v[2:5], v[152:155], v[204:207], v[2:5]
	v_mfma_f32_16x16x32_bf16 v[72:75], v[156:159], v[172:175], v[72:75]
	v_mfma_f32_16x16x32_bf16 v[56:59], v[164:167], v[172:175], v[56:59]
	v_mfma_f32_16x16x32_bf16 v[48:51], v[156:159], v[180:183], v[48:51]
	v_mfma_f32_16x16x32_bf16 v[40:43], v[164:167], v[180:183], v[40:43]
	v_mfma_f32_16x16x32_bf16 v[32:35], v[156:159], v[188:191], v[32:35]
	v_mfma_f32_16x16x32_bf16 v[24:27], v[164:167], v[188:191], v[24:27]
	v_mfma_f32_16x16x32_bf16 v[16:19], v[156:159], v[200:203], v[16:19]
	v_mfma_f32_16x16x32_bf16 v[6:9], v[164:167], v[200:203], v[8:11]
	v_mfma_f32_16x16x32_bf16 v[72:75], v[160:163], v[176:179], v[72:75]
	v_mfma_f32_16x16x32_bf16 v[56:59], v[168:171], v[176:179], v[56:59]
	v_mfma_f32_16x16x32_bf16 v[48:51], v[160:163], v[184:187], v[48:51]
	v_mfma_f32_16x16x32_bf16 v[40:43], v[168:171], v[184:187], v[40:43]
	v_mfma_f32_16x16x32_bf16 v[32:35], v[160:163], v[192:195], v[32:35]
	v_mfma_f32_16x16x32_bf16 v[24:27], v[168:171], v[192:195], v[24:27]
	v_mfma_f32_16x16x32_bf16 v[16:19], v[160:163], v[204:207], v[16:19]
	v_mfma_f32_16x16x32_bf16 v[8:11], v[168:171], v[204:207], v[6:9]
	s_barrier
	s_setprio 0
	s_mov_b32 m0, s44
	s_nop 0
	buffer_load_dwordx4 v132, s[20:23], s59 offen lds
	s_mov_b32 m0, s36
	s_nop 0
	buffer_load_dwordx4 v134, s[20:23], s59 offen lds
	v_add_u32_e32 v140, 0x18000, v136
	v_add_u32_e32 v141, 0x1c000, v136
	ds_read_b128 v[142:145], v140
	ds_read_b128 v[146:149], v140 offset:1024
	ds_read_b128 v[150:153], v140 offset:2048
	ds_read_b128 v[154:157], v140 offset:3072
	ds_read_b128 v[158:161], v141
	ds_read_b128 v[162:165], v141 offset:1024
	ds_read_b128 v[166:169], v141 offset:2048
	ds_read_b128 v[170:173], v141 offset:3072
	s_add_i32 s59, s59, 0x40000
	s_mov_b32 m0, s37
	ds_read_b128 v[174:177], v137 offset:32768
	ds_read_b128 v[178:181], v137 offset:33792
	ds_read_b128 v[182:185], v137 offset:34816
	ds_read_b128 v[186:189], v137 offset:35840
	ds_read_b128 v[190:193], v137 offset:36864
	ds_read_b128 v[194:197], v137 offset:37888
	ds_read_b128 v[200:203], v137 offset:38912
	ds_read_b128 v[204:207], v137 offset:39936
	buffer_load_dwordx4 v132, s[20:23], s59 offen lds
	s_mov_b32 m0, s38
	s_nop 0
	buffer_load_dwordx4 v134, s[20:23], s59 offen lds
	s_waitcnt vmcnt(8)
	s_waitcnt lgkmcnt(0)
	s_setprio 1
	s_barrier
	v_mfma_f32_16x16x32_bf16 v[124:127], v[142:145], v[174:177], v[124:127]
	v_mfma_f32_16x16x32_bf16 v[116:119], v[150:153], v[174:177], v[116:119]
	v_mfma_f32_16x16x32_bf16 v[108:111], v[142:145], v[182:185], v[108:111]
	v_mfma_f32_16x16x32_bf16 v[100:103], v[150:153], v[182:185], v[100:103]
	v_mfma_f32_16x16x32_bf16 v[92:95], v[142:145], v[190:193], v[92:95]
	v_mfma_f32_16x16x32_bf16 v[84:87], v[150:153], v[190:193], v[84:87]
	v_mfma_f32_16x16x32_bf16 v[76:79], v[142:145], v[200:203], v[76:79]
	v_mfma_f32_16x16x32_bf16 v[64:67], v[150:153], v[200:203], v[64:67]
	v_mfma_f32_16x16x32_bf16 v[124:127], v[146:149], v[178:181], v[124:127]
	v_mfma_f32_16x16x32_bf16 v[116:119], v[154:157], v[178:181], v[116:119]
	v_mfma_f32_16x16x32_bf16 v[108:111], v[146:149], v[186:189], v[108:111]
	v_mfma_f32_16x16x32_bf16 v[100:103], v[154:157], v[186:189], v[100:103]
	v_mfma_f32_16x16x32_bf16 v[92:95], v[146:149], v[194:197], v[92:95]
	v_mfma_f32_16x16x32_bf16 v[84:87], v[154:157], v[194:197], v[84:87]
	v_mfma_f32_16x16x32_bf16 v[76:79], v[146:149], v[204:207], v[76:79]
	v_mfma_f32_16x16x32_bf16 v[64:67], v[154:157], v[204:207], v[64:67]
	v_mfma_f32_16x16x32_bf16 v[128:131], v[158:161], v[174:177], v[128:131]
	v_mfma_f32_16x16x32_bf16 v[120:123], v[166:169], v[174:177], v[120:123]
	v_mfma_f32_16x16x32_bf16 v[112:115], v[158:161], v[182:185], v[112:115]
	v_mfma_f32_16x16x32_bf16 v[104:107], v[166:169], v[182:185], v[104:107]
	v_mfma_f32_16x16x32_bf16 v[96:99], v[158:161], v[190:193], v[96:99]
	v_mfma_f32_16x16x32_bf16 v[88:91], v[166:169], v[190:193], v[88:91]
	v_mfma_f32_16x16x32_bf16 v[80:83], v[158:161], v[200:203], v[80:83]
	v_mfma_f32_16x16x32_bf16 v[68:71], v[166:169], v[200:203], v[68:71]
	v_mfma_f32_16x16x32_bf16 v[128:131], v[162:165], v[178:181], v[128:131]
	v_mfma_f32_16x16x32_bf16 v[120:123], v[170:173], v[178:181], v[120:123]
	v_mfma_f32_16x16x32_bf16 v[112:115], v[162:165], v[186:189], v[112:115]
	v_mfma_f32_16x16x32_bf16 v[104:107], v[170:173], v[186:189], v[104:107]
	v_mfma_f32_16x16x32_bf16 v[96:99], v[162:165], v[194:197], v[96:99]
	v_mfma_f32_16x16x32_bf16 v[88:91], v[170:173], v[194:197], v[88:91]
	v_mfma_f32_16x16x32_bf16 v[80:83], v[162:165], v[204:207], v[80:83]
	v_mfma_f32_16x16x32_bf16 v[68:71], v[170:173], v[204:207], v[68:71]
	s_barrier
; #define PG8_STAGE(bufoff, gbase, voff) do { const Src _g = (gbase); _Pragma("unroll") for (int _i = 0; _i < 2; ++_i) \
;         __builtin_amdgcn_raw_ptr_buffer_load_lds(_g.r, (LAS unsigned*)(lds + (bufoff) + ldsw + _i * 8192), 16, (voff)[_i], _g.o, 0, 0); } while (0)
; #define PG8_WAIT_V(n) asm volatile("s_waitcnt vmcnt(" #n ")" ::: "memory")
; template <class Epi, bool ALIGN_EPI, bool SP2, class Hook>
; __device__ __forceinline__ void gemm_phase(LAS unsigned char* lds, const Gemm g, const StaticOrder& S, const Epi& E, Acc& acc, const bool fresh, const Hook& H, const int wave_id) {
;     ...
;         for (int t = t0; t < nt; t += 2) {
;             const bool last = (t == nt - 2);
;             const Src a1 = cA + (size_t)(t + 1) * kstep;
;             const Src a2 = last ? nA : cA + (size_t)(t + 2) * kstep, b2 = last ? nB : cB + (size_t)(t + 2) * kstep;
;             const Src a3 = a2 + kstep, b3 = b2 + kstep;
;             if (last && has_next) H(nxt);
;             if constexpr (SP2) {
;             PG8_TRIP_SP2(PG8_WAIT_V(8));
;             } else {
;             PG8_LDB(B0, 0, 0); PG8_SCHED; PG8_LDA(At, 0, 0); PG8_STAGE(PG8_SA(1, 1), a1 + hstepA, voffA);
;             PG8_WAIT_L(8); PG8_BAR; PG8_WAIT_L(0); PG8_MMA(0, 0, At, B0); PG8_BAR; PG8_SCHED;
;             PG8_LDB(B1, 0, 1); PG8_STAGE(PG8_SB(0, 0), b2, voffB);
;             PG8_BAR; PG8_WAIT_L(0); PG8_MMA(0, 1, At, B1); PG8_BAR;
;             PG8_LDA(At, 0, 1); PG8_STAGE(PG8_SA(0, 0), a2, voffA);
;             PG8_BAR; PG8_WAIT_L(0); PG8_MMA(1, 0, At, B0); PG8_BAR; PG8_SCHED;
;             PG8_STAGE(PG8_SB(0, 1), b2 + hstep, voffB);
;             PG8_WAIT_V(6); PG8_BAR; PG8_MMA(1, 1, At, B1); PG8_BAR;
;             PG8_LDB(B0, 1, 0); PG8_SCHED; PG8_LDA(At, 1, 0); PG8_STAGE(PG8_SA(0, 1), a2 + hstepA, voffA);
;             PG8_WAIT_L(8); PG8_BAR; PG8_WAIT_L(0); PG8_MMA(0, 0, At, B0); PG8_BAR; PG8_SCHED;
;             PG8_LDB(B1, 1, 1); PG8_STAGE(PG8_SB(1, 0), b3, voffB);
;             PG8_BAR; PG8_WAIT_L(0); PG8_MMA(0, 1, At, B1); PG8_BAR;
;             PG8_LDA(At, 1, 1); PG8_STAGE(PG8_SA(1, 0), a3, voffA);
;             PG8_BAR; PG8_WAIT_L(0); PG8_MMA(1, 0, At, B0); PG8_BAR; PG8_SCHED;
;             PG8_STAGE(PG8_SB(1, 1), b3 + hstep, voffB);
;             PG8_WAIT_V(6); PG8_BAR; PG8_MMA(1, 1, At, B1); PG8_BAR;
;             }
;         }
;         if constexpr (ALIGN_EPI) { if (wr == 0) PG8_BAR; }
	s_setprio 0
	s_mov_b32 m0, s39
	s_or_b32 s59, s57, 0x80
	ds_read_b128 v[174:177], v137 offset:49152
	ds_read_b128 v[178:181], v137 offset:50176
	ds_read_b128 v[182:185], v137 offset:51200
	ds_read_b128 v[186:189], v137 offset:52224
	ds_read_b128 v[190:193], v137 offset:53248
	ds_read_b128 v[194:197], v137 offset:54272
	ds_read_b128 v[200:203], v137 offset:55296
	ds_read_b128 v[204:207], v137 offset:56320
	buffer_load_dwordx4 v133, s[16:19], s59 offen lds
	s_mov_b32 m0, s40
	s_add_i32 s57, s57, 0x40080
	buffer_load_dwordx4 v135, s[16:19], s59 offen lds
	s_mov_b32 m0, s43
	s_nop 0
	buffer_load_dwordx4 v133, s[16:19], s57 offen lds
	s_mov_b32 m0, s42
	s_nop 0
	buffer_load_dwordx4 v135, s[16:19], s57 offen lds
	s_waitcnt vmcnt(6)
	s_waitcnt lgkmcnt(0)
	s_setprio 1
	s_barrier
	v_mfma_f32_16x16x32_bf16 v[60:63], v[142:145], v[174:177], v[60:63]
	v_mfma_f32_16x16x32_bf16 v[52:55], v[150:153], v[174:177], v[52:55]
	v_mfma_f32_16x16x32_bf16 v[44:47], v[142:145], v[182:185], v[44:47]
	v_mfma_f32_16x16x32_bf16 v[36:39], v[150:153], v[182:185], v[36:39]
	v_mfma_f32_16x16x32_bf16 v[28:31], v[142:145], v[190:193], v[28:31]
	v_mfma_f32_16x16x32_bf16 v[20:23], v[150:153], v[190:193], v[20:23]
	v_mfma_f32_16x16x32_bf16 v[12:15], v[142:145], v[200:203], v[12:15]
	v_mfma_f32_16x16x32_bf16 v[2:5], v[150:153], v[200:203], v[2:5]
	v_mfma_f32_16x16x32_bf16 v[60:63], v[146:149], v[178:181], v[60:63]
	v_mfma_f32_16x16x32_bf16 v[52:55], v[154:157], v[178:181], v[52:55]
	v_mfma_f32_16x16x32_bf16 v[44:47], v[146:149], v[186:189], v[44:47]
	v_mfma_f32_16x16x32_bf16 v[36:39], v[154:157], v[186:189], v[36:39]
	v_mfma_f32_16x16x32_bf16 v[28:31], v[146:149], v[194:197], v[28:31]
	v_mfma_f32_16x16x32_bf16 v[20:23], v[154:157], v[194:197], v[20:23]
	v_mfma_f32_16x16x32_bf16 v[12:15], v[146:149], v[204:207], v[12:15]
	v_mfma_f32_16x16x32_bf16 v[4:7], v[154:157], v[204:207], v[2:5]
	v_mfma_f32_16x16x32_bf16 v[72:75], v[158:161], v[174:177], v[72:75]
	v_mfma_f32_16x16x32_bf16 v[56:59], v[166:169], v[174:177], v[56:59]
	v_mfma_f32_16x16x32_bf16 v[48:51], v[158:161], v[182:185], v[48:51]
	v_mfma_f32_16x16x32_bf16 v[40:43], v[166:169], v[182:185], v[40:43]
	v_mfma_f32_16x16x32_bf16 v[32:35], v[158:161], v[190:193], v[32:35]
	v_mfma_f32_16x16x32_bf16 v[24:27], v[166:169], v[190:193], v[24:27]
	v_mfma_f32_16x16x32_bf16 v[16:19], v[158:161], v[200:203], v[16:19]
	v_mfma_f32_16x16x32_bf16 v[8:11], v[166:169], v[200:203], v[8:11]
	v_mfma_f32_16x16x32_bf16 v[72:75], v[162:165], v[178:181], v[72:75]
	v_mfma_f32_16x16x32_bf16 v[56:59], v[170:173], v[178:181], v[56:59]
	v_mfma_f32_16x16x32_bf16 v[48:51], v[162:165], v[186:189], v[48:51]
	v_mfma_f32_16x16x32_bf16 v[40:43], v[170:173], v[186:189], v[40:43]
	v_mfma_f32_16x16x32_bf16 v[32:35], v[162:165], v[194:197], v[32:35]
	v_mfma_f32_16x16x32_bf16 v[24:27], v[170:173], v[194:197], v[24:27]
	v_mfma_f32_16x16x32_bf16 v[16:19], v[162:165], v[204:207], v[16:19]
	v_mfma_f32_16x16x32_bf16 v[8:11], v[170:173], v[204:207], v[8:11]
	s_barrier
	s_setprio 0
	s_add_i32 s54, s54, 2
	s_addk_i32 s55, 0x100
	s_addk_i32 s56, 0x100
	s_cmp_gt_u32 s54, 13
	s_cbranch_scc0 .LBB0_1461
	s_mov_b32 m0, s41
	s_nop 0
	buffer_load_dwordx4 v132, s[20:23], s58 offen lds
	s_mov_b32 m0, s33
	s_nop 0
	buffer_load_dwordx4 v134, s[20:23], s58 offen lds
	v_readlane_b32 s12, v251, 45
	v_readlane_b32 s13, v251, 46
	s_and_b64 vcc, exec, s[12:13]
	s_cbranch_vccz .LBB0_1464
	s_barrier

; #define PG8_WAIT_V(n) asm volatile("s_waitcnt vmcnt(" #n ")" ::: "memory")
; template <class Epi, bool ALIGN_EPI, bool SP2, class Hook>
; __device__ __forceinline__ void gemm_phase(LAS unsigned char* lds, const Gemm g, const StaticOrder& S, const Epi& E, Acc& acc, const bool fresh, const Hook& H, const int wave_id) {
;     ...
;         for (int t = t0; t < nt; t += 2) {
;             const bool last = (t == nt - 2);
;             const Src a1 = cA + (size_t)(t + 1) * kstep;
;             const Src a2 = last ? nA : cA + (size_t)(t + 2) * kstep, b2 = last ? nB : cB + (size_t)(t + 2) * kstep;
;             const Src a3 = a2 + kstep, b3 = b2 + kstep;
;             if (last && has_next) H(nxt);
;             if constexpr (SP2) {
;             PG8_TRIP_SP2(PG8_WAIT_V(8));
.LBB0_1572:
	s_add_i32 s100, s2, 0xfff40000
	v_add_u32_e32 v142, 0x10000, v161
	v_add_u32_e32 v163, 0x14000, v161
	ds_read_b128 v[130:133], v142
	ds_read_b128 v[134:137], v142 offset:1024
	ds_read_b128 v[138:141], v142 offset:2048
	ds_read_b128 v[142:145], v142 offset:3072
	ds_read_b128 v[146:149], v163
	ds_read_b128 v[150:153], v163 offset:1024
	ds_read_b128 v[154:157], v163 offset:2048
	ds_read_b128 v[164:167], v163 offset:3072
	s_add_i32 s16, s2, 0xfff40080
	s_cmp_eq_u32 s61, 40
	s_cselect_b32 s64, s57, s16
	s_cselect_b32 s17, s35, s9
	s_cselect_b32 s16, s34, s8
	s_cselect_b32 s19, s51, s53
	s_cselect_b32 s18, s50, s52
	s_cselect_b32 s62, s58, s3
	s_cselect_b32 s20, s10, s12
	s_cselect_b32 s21, s11, s13
	s_cselect_b32 s22, s30, s14
	s_cselect_b32 s23, s31, s15
	s_or_b32 s63, s64, 0x80
	s_mov_b32 m0, s41
	s_nop 0
	buffer_load_dwordx4 v0, s[12:15], s100 offen lds
	s_mov_b32 m0, s33
	s_nop 0
	buffer_load_dwordx4 v159, s[12:15], s100 offen lds
	s_mov_b32 m0, s45
	ds_read_b128 v[168:171], v162
	ds_read_b128 v[172:175], v162 offset:1024
	ds_read_b128 v[176:179], v162 offset:2048
	ds_read_b128 v[180:183], v162 offset:3072
	ds_read_b128 v[184:187], v162 offset:4096
	ds_read_b128 v[188:191], v162 offset:5120
	ds_read_b128 v[192:195], v162 offset:6144
	ds_read_b128 v[200:203], v162 offset:7168
	buffer_load_dwordx4 v0, s[12:15], s2 offen lds
	s_mov_b32 m0, s46
	s_nop 0
	buffer_load_dwordx4 v159, s[12:15], s2 offen lds
	s_waitcnt vmcnt(8)
	s_waitcnt lgkmcnt(0)
	s_setprio 1
	s_barrier
	v_mfma_f32_16x16x32_bf16 v[126:129], v[130:133], v[168:171], v[126:129]
	v_mfma_f32_16x16x32_bf16 v[122:125], v[138:141], v[168:171], v[122:125]
	v_mfma_f32_16x16x32_bf16 v[110:113], v[130:133], v[176:179], v[110:113]
	v_mfma_f32_16x16x32_bf16 v[106:109], v[138:141], v[176:179], v[106:109]
	v_mfma_f32_16x16x32_bf16 v[94:97], v[130:133], v[184:187], v[94:97]
	v_mfma_f32_16x16x32_bf16 v[90:93], v[138:141], v[184:187], v[90:93]
	v_mfma_f32_16x16x32_bf16 v[78:81], v[130:133], v[192:195], v[78:81]
	v_mfma_f32_16x16x32_bf16 v[74:77], v[138:141], v[192:195], v[74:77]
	v_mfma_f32_16x16x32_bf16 v[126:129], v[134:137], v[172:175], v[126:129]
	v_mfma_f32_16x16x32_bf16 v[122:125], v[142:145], v[172:175], v[122:125]
	v_mfma_f32_16x16x32_bf16 v[110:113], v[134:137], v[180:183], v[110:113]
	v_mfma_f32_16x16x32_bf16 v[106:109], v[142:145], v[180:183], v[106:109]
	v_mfma_f32_16x16x32_bf16 v[94:97], v[134:137], v[188:191], v[94:97]
	v_mfma_f32_16x16x32_bf16 v[90:93], v[142:145], v[188:191], v[90:93]
	v_mfma_f32_16x16x32_bf16 v[78:81], v[134:137], v[200:203], v[78:81]
	v_mfma_f32_16x16x32_bf16 v[74:77], v[142:145], v[200:203], v[74:77]
	v_mfma_f32_16x16x32_bf16 v[118:121], v[146:149], v[168:171], v[118:121]
	v_mfma_f32_16x16x32_bf16 v[114:117], v[154:157], v[168:171], v[114:117]
	v_mfma_f32_16x16x32_bf16 v[102:105], v[146:149], v[176:179], v[102:105]
	v_mfma_f32_16x16x32_bf16 v[98:101], v[154:157], v[176:179], v[98:101]
	v_mfma_f32_16x16x32_bf16 v[86:89], v[146:149], v[184:187], v[86:89]
	v_mfma_f32_16x16x32_bf16 v[82:85], v[154:157], v[184:187], v[82:85]
	v_mfma_f32_16x16x32_bf16 v[70:73], v[146:149], v[192:195], v[70:73]
	v_mfma_f32_16x16x32_bf16 v[66:69], v[154:157], v[192:195], v[66:69]
	v_mfma_f32_16x16x32_bf16 v[118:121], v[150:153], v[172:175], v[118:121]
	v_mfma_f32_16x16x32_bf16 v[114:117], v[164:167], v[172:175], v[114:117]
	v_mfma_f32_16x16x32_bf16 v[102:105], v[150:153], v[180:183], v[102:105]
	v_mfma_f32_16x16x32_bf16 v[98:101], v[164:167], v[180:183], v[98:101]
	v_mfma_f32_16x16x32_bf16 v[86:89], v[150:153], v[188:191], v[86:89]
	v_mfma_f32_16x16x32_bf16 v[82:85], v[164:167], v[188:191], v[82:85]
	v_mfma_f32_16x16x32_bf16 v[70:73], v[150:153], v[200:203], v[70:73]
	v_mfma_f32_16x16x32_bf16 v[66:69], v[164:167], v[200:203], v[66:69]
	s_barrier
	s_setprio 0
	s_mov_b32 m0, s92
	ds_read_b128 v[168:171], v162 offset:16384
	ds_read_b128 v[172:175], v162 offset:17408
	ds_read_b128 v[176:179], v162 offset:18432
	ds_read_b128 v[180:183], v162 offset:19456
	ds_read_b128 v[184:187], v162 offset:20480
	ds_read_b128 v[188:191], v162 offset:21504
	ds_read_b128 v[192:195], v162 offset:22528
	ds_read_b128 v[200:203], v162 offset:23552
	buffer_load_dwordx4 v158, s[16:19], s62 offen lds
	s_mov_b32 m0, s93
	s_add_i32 s65, s62, 0xb0000
	buffer_load_dwordx4 v160, s[16:19], s62 offen lds
	s_mov_b32 m0, s94
	s_nop 0
	buffer_load_dwordx4 v158, s[16:19], s65 offen lds
	s_mov_b32 m0, s95
	s_nop 0
	buffer_load_dwordx4 v160, s[16:19], s65 offen lds
	s_waitcnt vmcnt(6)
	s_waitcnt lgkmcnt(0)
	s_setprio 1
	s_barrier
	v_mfma_f32_16x16x32_bf16 v[62:65], v[130:133], v[168:171], v[62:65]
	v_mfma_f32_16x16x32_bf16 v[58:61], v[138:141], v[168:171], v[58:61]
	v_mfma_f32_16x16x32_bf16 v[46:49], v[130:133], v[176:179], v[46:49]
	v_mfma_f32_16x16x32_bf16 v[42:45], v[138:141], v[176:179], v[42:45]
	v_mfma_f32_16x16x32_bf16 v[30:33], v[130:133], v[184:187], v[30:33]
	v_mfma_f32_16x16x32_bf16 v[26:29], v[138:141], v[184:187], v[26:29]
	v_mfma_f32_16x16x32_bf16 v[14:17], v[130:133], v[192:195], v[14:17]
	v_mfma_f32_16x16x32_bf16 v[10:13], v[138:141], v[192:195], v[10:13]
	v_mfma_f32_16x16x32_bf16 v[62:65], v[134:137], v[172:175], v[62:65]
	v_mfma_f32_16x16x32_bf16 v[58:61], v[142:145], v[172:175], v[58:61]
	v_mfma_f32_16x16x32_bf16 v[46:49], v[134:137], v[180:183], v[46:49]
	v_mfma_f32_16x16x32_bf16 v[42:45], v[142:145], v[180:183], v[42:45]
	v_mfma_f32_16x16x32_bf16 v[30:33], v[134:137], v[188:191], v[30:33]
	v_mfma_f32_16x16x32_bf16 v[26:29], v[142:145], v[188:191], v[26:29]
	v_mfma_f32_16x16x32_bf16 v[14:17], v[134:137], v[200:203], v[14:17]
	v_mfma_f32_16x16x32_bf16 v[10:13], v[142:145], v[200:203], v[10:13]
	v_mfma_f32_16x16x32_bf16 v[54:57], v[146:149], v[168:171], v[54:57]
	v_mfma_f32_16x16x32_bf16 v[50:53], v[154:157], v[168:171], v[50:53]
	v_mfma_f32_16x16x32_bf16 v[38:41], v[146:149], v[176:179], v[38:41]
	v_mfma_f32_16x16x32_bf16 v[34:37], v[154:157], v[176:179], v[34:37]
	v_mfma_f32_16x16x32_bf16 v[22:25], v[146:149], v[184:187], v[22:25]
	v_mfma_f32_16x16x32_bf16 v[18:21], v[154:157], v[184:187], v[18:21]
	v_mfma_f32_16x16x32_bf16 v[6:9], v[146:149], v[192:195], v[6:9]
	v_mfma_f32_16x16x32_bf16 v[2:5], v[154:157], v[192:195], v[2:5]
	v_mfma_f32_16x16x32_bf16 v[54:57], v[150:153], v[172:175], v[54:57]
	v_mfma_f32_16x16x32_bf16 v[50:53], v[164:167], v[172:175], v[50:53]
	v_mfma_f32_16x16x32_bf16 v[38:41], v[150:153], v[180:183], v[38:41]
	v_mfma_f32_16x16x32_bf16 v[34:37], v[164:167], v[180:183], v[34:37]
	v_mfma_f32_16x16x32_bf16 v[22:25], v[150:153], v[188:191], v[22:25]
	v_mfma_f32_16x16x32_bf16 v[18:21], v[164:167], v[188:191], v[18:21]
	v_mfma_f32_16x16x32_bf16 v[6:9], v[150:153], v[200:203], v[6:9]
	v_mfma_f32_16x16x32_bf16 v[2:5], v[164:167], v[200:203], v[2:5]
	s_barrier
; #define PG8_STAGE(bufoff, gbase, voff) do { const Src _g = (gbase); _Pragma("unroll") for (int _i = 0; _i < 2; ++_i) \
;         __builtin_amdgcn_raw_ptr_buffer_load_lds(_g.r, (LAS unsigned*)(lds + (bufoff) + ldsw + _i * 8192), 16, (voff)[_i], _g.o, 0, 0); } while (0)
; #define PG8_WAIT_V(n) asm volatile("s_waitcnt vmcnt(" #n ")" ::: "memory")
; template <class Epi, bool ALIGN_EPI, bool SP2, class Hook>
; __device__ __forceinline__ void gemm_phase(LAS unsigned char* lds, const Gemm g, const StaticOrder& S, const Epi& E, Acc& acc, const bool fresh, const Hook& H, const int wave_id) {
;     ...
;         for (int t = t0; t < nt; t += 2) {
;             const bool last = (t == nt - 2);
;             const Src a1 = cA + (size_t)(t + 1) * kstep;
;             const Src a2 = last ? nA : cA + (size_t)(t + 2) * kstep, b2 = last ? nB : cB + (size_t)(t + 2) * kstep;
;             const Src a3 = a2 + kstep, b3 = b2 + kstep;
;             if (last && has_next) H(nxt);
;             if constexpr (SP2) {
;             PG8_TRIP_SP2(PG8_WAIT_V(8));
;             } else {
;             PG8_LDB(B0, 0, 0); PG8_SCHED; PG8_LDA(At, 0, 0); PG8_STAGE(PG8_SA(1, 1), a1 + hstepA, voffA);
;             PG8_WAIT_L(8); PG8_BAR; PG8_WAIT_L(0); PG8_MMA(0, 0, At, B0); PG8_BAR; PG8_SCHED;
;             PG8_LDB(B1, 0, 1); PG8_STAGE(PG8_SB(0, 0), b2, voffB);
;             PG8_BAR; PG8_WAIT_L(0); PG8_MMA(0, 1, At, B1); PG8_BAR;
;             PG8_LDA(At, 0, 1); PG8_STAGE(PG8_SA(0, 0), a2, voffA);
;             PG8_BAR; PG8_WAIT_L(0); PG8_MMA(1, 0, At, B0); PG8_BAR; PG8_SCHED;
;             PG8_STAGE(PG8_SB(0, 1), b2 + hstep, voffB);
;             PG8_WAIT_V(6); PG8_BAR; PG8_MMA(1, 1, At, B1); PG8_BAR;
;             PG8_LDB(B0, 1, 0); PG8_SCHED; PG8_LDA(At, 1, 0); PG8_STAGE(PG8_SA(0, 1), a2 + hstepA, voffA);
;             PG8_WAIT_L(8); PG8_BAR; PG8_WAIT_L(0); PG8_MMA(0, 0, At, B0); PG8_BAR; PG8_SCHED;
;             PG8_LDB(B1, 1, 1); PG8_STAGE(PG8_SB(1, 0), b3, voffB);
;             PG8_BAR; PG8_WAIT_L(0); PG8_MMA(0, 1, At, B1); PG8_BAR;
;             PG8_LDA(At, 1, 1); PG8_STAGE(PG8_SA(1, 0), a3, voffA);
;             PG8_BAR; PG8_WAIT_L(0); PG8_MMA(1, 0, At, B0); PG8_BAR; PG8_SCHED;
;             PG8_STAGE(PG8_SB(1, 1), b3 + hstep, voffB);
;             PG8_WAIT_V(6); PG8_BAR; PG8_MMA(1, 1, At, B1); PG8_BAR;
;             }
;         }
;         if constexpr (ALIGN_EPI) { if (wr == 0) PG8_BAR; }
	s_setprio 0
	s_mov_b32 m0, s44
	s_nop 0
	buffer_load_dwordx4 v0, s[20:23], s64 offen lds
	s_mov_b32 m0, s36
	s_nop 0
	buffer_load_dwordx4 v159, s[20:23], s64 offen lds
	v_add_u32_e32 v142, 0x18000, v161
	v_add_u32_e32 v163, 0x1c000, v161
	ds_read_b128 v[130:133], v142
	ds_read_b128 v[134:137], v142 offset:1024
	ds_read_b128 v[138:141], v142 offset:2048
	ds_read_b128 v[142:145], v142 offset:3072
	ds_read_b128 v[146:149], v163
	ds_read_b128 v[150:153], v163 offset:1024
	ds_read_b128 v[154:157], v163 offset:2048
	ds_read_b128 v[164:167], v163 offset:3072
	s_add_i32 s64, s64, 0xc0000
	s_mov_b32 m0, s37
	ds_read_b128 v[168:171], v162 offset:32768
	ds_read_b128 v[172:175], v162 offset:33792
	ds_read_b128 v[176:179], v162 offset:34816
	ds_read_b128 v[180:183], v162 offset:35840
	ds_read_b128 v[184:187], v162 offset:36864
	ds_read_b128 v[188:191], v162 offset:37888
	ds_read_b128 v[192:195], v162 offset:38912
	ds_read_b128 v[200:203], v162 offset:39936
	buffer_load_dwordx4 v0, s[20:23], s64 offen lds
	s_mov_b32 m0, s38
	s_nop 0
	buffer_load_dwordx4 v159, s[20:23], s64 offen lds
	s_waitcnt vmcnt(8)
	s_waitcnt lgkmcnt(0)
	s_setprio 1
	s_barrier
	v_mfma_f32_16x16x32_bf16 v[126:129], v[130:133], v[168:171], v[126:129]
	v_mfma_f32_16x16x32_bf16 v[122:125], v[138:141], v[168:171], v[122:125]
	v_mfma_f32_16x16x32_bf16 v[110:113], v[130:133], v[176:179], v[110:113]
	v_mfma_f32_16x16x32_bf16 v[106:109], v[138:141], v[176:179], v[106:109]
	v_mfma_f32_16x16x32_bf16 v[94:97], v[130:133], v[184:187], v[94:97]
	v_mfma_f32_16x16x32_bf16 v[90:93], v[138:141], v[184:187], v[90:93]
	v_mfma_f32_16x16x32_bf16 v[78:81], v[130:133], v[192:195], v[78:81]
	v_mfma_f32_16x16x32_bf16 v[74:77], v[138:141], v[192:195], v[74:77]
	v_mfma_f32_16x16x32_bf16 v[126:129], v[134:137], v[172:175], v[126:129]
	v_mfma_f32_16x16x32_bf16 v[122:125], v[142:145], v[172:175], v[122:125]
	v_mfma_f32_16x16x32_bf16 v[110:113], v[134:137], v[180:183], v[110:113]
	v_mfma_f32_16x16x32_bf16 v[106:109], v[142:145], v[180:183], v[106:109]
	v_mfma_f32_16x16x32_bf16 v[94:97], v[134:137], v[188:191], v[94:97]
	v_mfma_f32_16x16x32_bf16 v[90:93], v[142:145], v[188:191], v[90:93]
	v_mfma_f32_16x16x32_bf16 v[78:81], v[134:137], v[200:203], v[78:81]
	v_mfma_f32_16x16x32_bf16 v[74:77], v[142:145], v[200:203], v[74:77]
	v_mfma_f32_16x16x32_bf16 v[118:121], v[146:149], v[168:171], v[118:121]
	v_mfma_f32_16x16x32_bf16 v[114:117], v[154:157], v[168:171], v[114:117]
	v_mfma_f32_16x16x32_bf16 v[102:105], v[146:149], v[176:179], v[102:105]
	v_mfma_f32_16x16x32_bf16 v[98:101], v[154:157], v[176:179], v[98:101]
	v_mfma_f32_16x16x32_bf16 v[86:89], v[146:149], v[184:187], v[86:89]
	v_mfma_f32_16x16x32_bf16 v[82:85], v[154:157], v[184:187], v[82:85]
	v_mfma_f32_16x16x32_bf16 v[70:73], v[146:149], v[192:195], v[70:73]
	v_mfma_f32_16x16x32_bf16 v[66:69], v[154:157], v[192:195], v[66:69]
	v_mfma_f32_16x16x32_bf16 v[118:121], v[150:153], v[172:175], v[118:121]
	v_mfma_f32_16x16x32_bf16 v[114:117], v[164:167], v[172:175], v[114:117]
	v_mfma_f32_16x16x32_bf16 v[102:105], v[150:153], v[180:183], v[102:105]
	v_mfma_f32_16x16x32_bf16 v[98:101], v[164:167], v[180:183], v[98:101]
	v_mfma_f32_16x16x32_bf16 v[86:89], v[150:153], v[188:191], v[86:89]
	v_mfma_f32_16x16x32_bf16 v[82:85], v[164:167], v[188:191], v[82:85]
	v_mfma_f32_16x16x32_bf16 v[70:73], v[150:153], v[200:203], v[70:73]
	v_mfma_f32_16x16x32_bf16 v[66:69], v[164:167], v[200:203], v[66:69]
	s_barrier
	s_setprio 0
	s_mov_b32 m0, s39
	s_or_b32 s64, s62, 0x80
	ds_read_b128 v[168:171], v162 offset:49152
	ds_read_b128 v[172:175], v162 offset:50176
	ds_read_b128 v[176:179], v162 offset:51200
	ds_read_b128 v[180:183], v162 offset:52224
	ds_read_b128 v[184:187], v162 offset:53248
	ds_read_b128 v[188:191], v162 offset:54272
	ds_read_b128 v[192:195], v162 offset:55296
	ds_read_b128 v[200:203], v162 offset:56320
	buffer_load_dwordx4 v158, s[16:19], s64 offen lds
	s_mov_b32 m0, s40
	s_add_i32 s62, s62, 0xb0080
	buffer_load_dwordx4 v160, s[16:19], s64 offen lds
	s_mov_b32 m0, s43
	s_nop 0
	buffer_load_dwordx4 v158, s[16:19], s62 offen lds
	s_mov_b32 m0, s42
	s_nop 0
	buffer_load_dwordx4 v160, s[16:19], s62 offen lds
	s_waitcnt vmcnt(6)
	s_waitcnt lgkmcnt(0)
	s_setprio 1
	s_barrier
	v_mfma_f32_16x16x32_bf16 v[62:65], v[130:133], v[168:171], v[62:65]
	v_mfma_f32_16x16x32_bf16 v[58:61], v[138:141], v[168:171], v[58:61]
	v_mfma_f32_16x16x32_bf16 v[46:49], v[130:133], v[176:179], v[46:49]
	v_mfma_f32_16x16x32_bf16 v[42:45], v[138:141], v[176:179], v[42:45]
	v_mfma_f32_16x16x32_bf16 v[30:33], v[130:133], v[184:187], v[30:33]
	v_mfma_f32_16x16x32_bf16 v[26:29], v[138:141], v[184:187], v[26:29]
	v_mfma_f32_16x16x32_bf16 v[14:17], v[130:133], v[192:195], v[14:17]
	v_mfma_f32_16x16x32_bf16 v[10:13], v[138:141], v[192:195], v[10:13]
	v_mfma_f32_16x16x32_bf16 v[62:65], v[134:137], v[172:175], v[62:65]
	v_mfma_f32_16x16x32_bf16 v[58:61], v[142:145], v[172:175], v[58:61]
	v_mfma_f32_16x16x32_bf16 v[46:49], v[134:137], v[180:183], v[46:49]
	v_mfma_f32_16x16x32_bf16 v[42:45], v[142:145], v[180:183], v[42:45]
	v_mfma_f32_16x16x32_bf16 v[30:33], v[134:137], v[188:191], v[30:33]
	v_mfma_f32_16x16x32_bf16 v[26:29], v[142:145], v[188:191], v[26:29]
	v_mfma_f32_16x16x32_bf16 v[14:17], v[134:137], v[200:203], v[14:17]
	v_mfma_f32_16x16x32_bf16 v[10:13], v[142:145], v[200:203], v[10:13]
	v_mfma_f32_16x16x32_bf16 v[54:57], v[146:149], v[168:171], v[54:57]
	v_mfma_f32_16x16x32_bf16 v[50:53], v[154:157], v[168:171], v[50:53]
	v_mfma_f32_16x16x32_bf16 v[38:41], v[146:149], v[176:179], v[38:41]
	v_mfma_f32_16x16x32_bf16 v[34:37], v[154:157], v[176:179], v[34:37]
	v_mfma_f32_16x16x32_bf16 v[22:25], v[146:149], v[184:187], v[22:25]
	v_mfma_f32_16x16x32_bf16 v[18:21], v[154:157], v[184:187], v[18:21]
	v_mfma_f32_16x16x32_bf16 v[6:9], v[146:149], v[192:195], v[6:9]
	v_mfma_f32_16x16x32_bf16 v[2:5], v[154:157], v[192:195], v[2:5]
	v_mfma_f32_16x16x32_bf16 v[54:57], v[150:153], v[172:175], v[54:57]
	v_mfma_f32_16x16x32_bf16 v[50:53], v[164:167], v[172:175], v[50:53]
	v_mfma_f32_16x16x32_bf16 v[38:41], v[150:153], v[180:183], v[38:41]
	v_mfma_f32_16x16x32_bf16 v[34:37], v[164:167], v[180:183], v[34:37]
	v_mfma_f32_16x16x32_bf16 v[22:25], v[150:153], v[188:191], v[22:25]
	v_mfma_f32_16x16x32_bf16 v[18:21], v[164:167], v[188:191], v[18:21]
	v_mfma_f32_16x16x32_bf16 v[6:9], v[150:153], v[200:203], v[6:9]
	v_mfma_f32_16x16x32_bf16 v[2:5], v[164:167], v[200:203], v[2:5]
	s_barrier
	s_setprio 0
	s_add_i32 s61, s61, 2
	s_addk_i32 s2, 0x100
	s_addk_i32 s3, 0x100
	s_cmp_gt_u32 s61, 41
	s_cbranch_scc0 .LBB0_1572
	s_mov_b32 m0, s41
	s_nop 0
	buffer_load_dwordx4 v0, s[20:23], s63 offen lds
	s_mov_b32 m0, s33
	s_nop 0
	buffer_load_dwordx4 v159, s[20:23], s63 offen lds
	v_readlane_b32 s2, v251, 45
	v_readlane_b32 s3, v251, 46
	s_and_b64 vcc, exec, s[2:3]
	s_cbranch_vccz .LBB0_1575
	s_barrier

; #define PG8_WAIT_V(n) asm volatile("s_waitcnt vmcnt(" #n ")" ::: "memory")
; template <class Epi, bool ALIGN_EPI, bool SP2, class Hook>
; __device__ __forceinline__ void gemm_phase(LAS unsigned char* lds, const Gemm g, const StaticOrder& S, const Epi& E, Acc& acc, const bool fresh, const Hook& H, const int wave_id) {
;     ...
;         for (int t = t0; t < nt; t += 2) {
;             const bool last = (t == nt - 2);
;             const Src a1 = cA + (size_t)(t + 1) * kstep;
;             const Src a2 = last ? nA : cA + (size_t)(t + 2) * kstep, b2 = last ? nB : cB + (size_t)(t + 2) * kstep;
;             const Src a3 = a2 + kstep, b3 = b2 + kstep;
;             if (last && has_next) H(nxt);
;             if constexpr (SP2) {
;             PG8_TRIP_SP2(PG8_WAIT_V(8));
.LBB0_1614:
	s_add_i32 s100, s2, 0xfff40000
	v_add_u32_e32 v0, 0x10000, v172
	ds_read_b128 v[130:133], v0
	ds_read_b128 v[134:137], v0 offset:1024
	ds_read_b128 v[138:141], v0 offset:2048
	ds_read_b128 v[142:145], v0 offset:3072
	v_add_u32_e32 v0, 0x14000, v172
	ds_read_b128 v[146:149], v0
	ds_read_b128 v[150:153], v0 offset:1024
	ds_read_b128 v[154:157], v0 offset:2048
	ds_read_b128 v[158:161], v0 offset:3072
	s_add_i32 s12, s2, 0xfff40080
	s_cmp_eq_u32 s59, 40
	s_cselect_b32 s62, s55, s12
	s_cselect_b32 s13, s31, s77
	s_cselect_b32 s12, s30, s76
	s_cselect_b32 s15, s35, s51
	s_cselect_b32 s14, s34, s50
	s_cselect_b32 s60, s56, s3
	s_cselect_b32 s16, s20, s8
	s_cselect_b32 s17, s21, s9
	s_cselect_b32 s18, s22, s10
	s_cselect_b32 s19, s23, s11
	s_or_b32 s61, s62, 0x80
	s_mov_b32 m0, s41
	s_nop 0
	buffer_load_dwordx4 v168, s[8:11], s100 offen lds
	s_mov_b32 m0, s33
	s_nop 0
	buffer_load_dwordx4 v170, s[8:11], s100 offen lds
	s_mov_b32 m0, s45
	ds_read_b128 v[162:165], v173
	ds_read_b128 v[174:177], v173 offset:1024
	ds_read_b128 v[178:181], v173 offset:2048
	ds_read_b128 v[182:185], v173 offset:3072
	ds_read_b128 v[186:189], v173 offset:4096
	ds_read_b128 v[190:193], v173 offset:5120
	ds_read_b128 v[194:197], v173 offset:6144
	ds_read_b128 v[200:203], v173 offset:7168
	buffer_load_dwordx4 v168, s[8:11], s2 offen lds
	s_mov_b32 m0, s46
	s_nop 0
	buffer_load_dwordx4 v170, s[8:11], s2 offen lds
	s_waitcnt vmcnt(8)
	s_waitcnt lgkmcnt(0)
	s_setprio 1
	s_barrier
	v_mfma_f32_16x16x32_bf16 v[126:129], v[130:133], v[162:165], v[126:129]
	v_mfma_f32_16x16x32_bf16 v[122:125], v[138:141], v[162:165], v[122:125]
	v_mfma_f32_16x16x32_bf16 v[110:113], v[130:133], v[178:181], v[110:113]
	v_mfma_f32_16x16x32_bf16 v[106:109], v[138:141], v[178:181], v[106:109]
	v_mfma_f32_16x16x32_bf16 v[94:97], v[130:133], v[186:189], v[94:97]
	v_mfma_f32_16x16x32_bf16 v[90:93], v[138:141], v[186:189], v[90:93]
	v_mfma_f32_16x16x32_bf16 v[78:81], v[130:133], v[194:197], v[78:81]
	v_mfma_f32_16x16x32_bf16 v[74:77], v[138:141], v[194:197], v[74:77]
	v_mfma_f32_16x16x32_bf16 v[126:129], v[134:137], v[174:177], v[126:129]
	v_mfma_f32_16x16x32_bf16 v[122:125], v[142:145], v[174:177], v[122:125]
	v_mfma_f32_16x16x32_bf16 v[110:113], v[134:137], v[182:185], v[110:113]
	v_mfma_f32_16x16x32_bf16 v[106:109], v[142:145], v[182:185], v[106:109]
	v_mfma_f32_16x16x32_bf16 v[94:97], v[134:137], v[190:193], v[94:97]
	v_mfma_f32_16x16x32_bf16 v[90:93], v[142:145], v[190:193], v[90:93]
	v_mfma_f32_16x16x32_bf16 v[78:81], v[134:137], v[200:203], v[78:81]
	v_mfma_f32_16x16x32_bf16 v[74:77], v[142:145], v[200:203], v[74:77]
	v_mfma_f32_16x16x32_bf16 v[118:121], v[146:149], v[162:165], v[118:121]
	v_mfma_f32_16x16x32_bf16 v[114:117], v[154:157], v[162:165], v[114:117]
	v_mfma_f32_16x16x32_bf16 v[102:105], v[146:149], v[178:181], v[102:105]
	v_mfma_f32_16x16x32_bf16 v[98:101], v[154:157], v[178:181], v[98:101]
	v_mfma_f32_16x16x32_bf16 v[86:89], v[146:149], v[186:189], v[86:89]
	v_mfma_f32_16x16x32_bf16 v[82:85], v[154:157], v[186:189], v[82:85]
	v_mfma_f32_16x16x32_bf16 v[70:73], v[146:149], v[194:197], v[70:73]
	v_mfma_f32_16x16x32_bf16 v[66:69], v[154:157], v[194:197], v[66:69]
	v_mfma_f32_16x16x32_bf16 v[118:121], v[150:153], v[174:177], v[118:121]
	v_mfma_f32_16x16x32_bf16 v[114:117], v[158:161], v[174:177], v[114:117]
	v_mfma_f32_16x16x32_bf16 v[102:105], v[150:153], v[182:185], v[102:105]
	v_mfma_f32_16x16x32_bf16 v[98:101], v[158:161], v[182:185], v[98:101]
	v_mfma_f32_16x16x32_bf16 v[86:89], v[150:153], v[190:193], v[86:89]
	v_mfma_f32_16x16x32_bf16 v[82:85], v[158:161], v[190:193], v[82:85]
	v_mfma_f32_16x16x32_bf16 v[70:73], v[150:153], v[200:203], v[70:73]
	v_mfma_f32_16x16x32_bf16 v[66:69], v[158:161], v[200:203], v[66:69]
	s_barrier
	s_setprio 0
	s_mov_b32 m0, s92
	ds_read_b128 v[162:165], v173 offset:16384
	ds_read_b128 v[174:177], v173 offset:17408
	ds_read_b128 v[178:181], v173 offset:18432
	ds_read_b128 v[182:185], v173 offset:19456
	ds_read_b128 v[186:189], v173 offset:20480
	ds_read_b128 v[190:193], v173 offset:21504
	ds_read_b128 v[194:197], v173 offset:22528
	ds_read_b128 v[200:203], v173 offset:23552
	buffer_load_dwordx4 v169, s[12:15], s60 offen lds
	s_mov_b32 m0, s93
	s_add_i32 s63, s60, 0xb0000
	buffer_load_dwordx4 v171, s[12:15], s60 offen lds
	s_mov_b32 m0, s94
	s_nop 0
	buffer_load_dwordx4 v169, s[12:15], s63 offen lds
	s_mov_b32 m0, s95
	s_nop 0
	buffer_load_dwordx4 v171, s[12:15], s63 offen lds
	s_waitcnt vmcnt(6)
	s_waitcnt lgkmcnt(0)
	s_setprio 1
	s_barrier
	v_mfma_f32_16x16x32_bf16 v[62:65], v[130:133], v[162:165], v[62:65]
	v_mfma_f32_16x16x32_bf16 v[58:61], v[138:141], v[162:165], v[58:61]
	v_mfma_f32_16x16x32_bf16 v[46:49], v[130:133], v[178:181], v[46:49]
	v_mfma_f32_16x16x32_bf16 v[42:45], v[138:141], v[178:181], v[42:45]
	v_mfma_f32_16x16x32_bf16 v[30:33], v[130:133], v[186:189], v[30:33]
	v_mfma_f32_16x16x32_bf16 v[26:29], v[138:141], v[186:189], v[26:29]
	v_mfma_f32_16x16x32_bf16 v[14:17], v[130:133], v[194:197], v[14:17]
	v_mfma_f32_16x16x32_bf16 v[10:13], v[138:141], v[194:197], v[10:13]
	v_mfma_f32_16x16x32_bf16 v[62:65], v[134:137], v[174:177], v[62:65]
	v_mfma_f32_16x16x32_bf16 v[58:61], v[142:145], v[174:177], v[58:61]
	v_mfma_f32_16x16x32_bf16 v[46:49], v[134:137], v[182:185], v[46:49]
	v_mfma_f32_16x16x32_bf16 v[42:45], v[142:145], v[182:185], v[42:45]
	v_mfma_f32_16x16x32_bf16 v[30:33], v[134:137], v[190:193], v[30:33]
	v_mfma_f32_16x16x32_bf16 v[26:29], v[142:145], v[190:193], v[26:29]
	v_mfma_f32_16x16x32_bf16 v[14:17], v[134:137], v[200:203], v[14:17]
	v_mfma_f32_16x16x32_bf16 v[10:13], v[142:145], v[200:203], v[10:13]
	v_mfma_f32_16x16x32_bf16 v[54:57], v[146:149], v[162:165], v[54:57]
	v_mfma_f32_16x16x32_bf16 v[50:53], v[154:157], v[162:165], v[50:53]
	v_mfma_f32_16x16x32_bf16 v[38:41], v[146:149], v[178:181], v[38:41]
	v_mfma_f32_16x16x32_bf16 v[34:37], v[154:157], v[178:181], v[34:37]
	v_mfma_f32_16x16x32_bf16 v[22:25], v[146:149], v[186:189], v[22:25]
	v_mfma_f32_16x16x32_bf16 v[18:21], v[154:157], v[186:189], v[18:21]
	v_mfma_f32_16x16x32_bf16 v[6:9], v[146:149], v[194:197], v[6:9]
	v_mfma_f32_16x16x32_bf16 v[2:5], v[154:157], v[194:197], v[2:5]
	v_mfma_f32_16x16x32_bf16 v[54:57], v[150:153], v[174:177], v[54:57]
	v_mfma_f32_16x16x32_bf16 v[50:53], v[158:161], v[174:177], v[50:53]
	v_mfma_f32_16x16x32_bf16 v[38:41], v[150:153], v[182:185], v[38:41]
	v_mfma_f32_16x16x32_bf16 v[34:37], v[158:161], v[182:185], v[34:37]
	v_mfma_f32_16x16x32_bf16 v[22:25], v[150:153], v[190:193], v[22:25]
	v_mfma_f32_16x16x32_bf16 v[18:21], v[158:161], v[190:193], v[18:21]
	v_mfma_f32_16x16x32_bf16 v[6:9], v[150:153], v[200:203], v[6:9]
	v_mfma_f32_16x16x32_bf16 v[2:5], v[158:161], v[200:203], v[2:5]
	s_barrier
; #define PG8_STAGE(bufoff, gbase, voff) do { const Src _g = (gbase); _Pragma("unroll") for (int _i = 0; _i < 2; ++_i) \
;         __builtin_amdgcn_raw_ptr_buffer_load_lds(_g.r, (LAS unsigned*)(lds + (bufoff) + ldsw + _i * 8192), 16, (voff)[_i], _g.o, 0, 0); } while (0)
; #define PG8_WAIT_V(n) asm volatile("s_waitcnt vmcnt(" #n ")" ::: "memory")
; template <class Epi, bool ALIGN_EPI, bool SP2, class Hook>
; __device__ __forceinline__ void gemm_phase(LAS unsigned char* lds, const Gemm g, const StaticOrder& S, const Epi& E, Acc& acc, const bool fresh, const Hook& H, const int wave_id) {
;     ...
;         for (int t = t0; t < nt; t += 2) {
;             const bool last = (t == nt - 2);
;             const Src a1 = cA + (size_t)(t + 1) * kstep;
;             const Src a2 = last ? nA : cA + (size_t)(t + 2) * kstep, b2 = last ? nB : cB + (size_t)(t + 2) * kstep;
;             const Src a3 = a2 + kstep, b3 = b2 + kstep;
;             if (last && has_next) H(nxt);
;             if constexpr (SP2) {
;             PG8_TRIP_SP2(PG8_WAIT_V(8));
;             } else {
;             PG8_LDB(B0, 0, 0); PG8_SCHED; PG8_LDA(At, 0, 0); PG8_STAGE(PG8_SA(1, 1), a1 + hstepA, voffA);
;             PG8_WAIT_L(8); PG8_BAR; PG8_WAIT_L(0); PG8_MMA(0, 0, At, B0); PG8_BAR; PG8_SCHED;
;             PG8_LDB(B1, 0, 1); PG8_STAGE(PG8_SB(0, 0), b2, voffB);
;             PG8_BAR; PG8_WAIT_L(0); PG8_MMA(0, 1, At, B1); PG8_BAR;
;             PG8_LDA(At, 0, 1); PG8_STAGE(PG8_SA(0, 0), a2, voffA);
;             PG8_BAR; PG8_WAIT_L(0); PG8_MMA(1, 0, At, B0); PG8_BAR; PG8_SCHED;
;             PG8_STAGE(PG8_SB(0, 1), b2 + hstep, voffB);
;             PG8_WAIT_V(6); PG8_BAR; PG8_MMA(1, 1, At, B1); PG8_BAR;
;             PG8_LDB(B0, 1, 0); PG8_SCHED; PG8_LDA(At, 1, 0); PG8_STAGE(PG8_SA(0, 1), a2 + hstepA, voffA);
;             PG8_WAIT_L(8); PG8_BAR; PG8_WAIT_L(0); PG8_MMA(0, 0, At, B0); PG8_BAR; PG8_SCHED;
;             PG8_LDB(B1, 1, 1); PG8_STAGE(PG8_SB(1, 0), b3, voffB);
;             PG8_BAR; PG8_WAIT_L(0); PG8_MMA(0, 1, At, B1); PG8_BAR;
;             PG8_LDA(At, 1, 1); PG8_STAGE(PG8_SA(1, 0), a3, voffA);
;             PG8_BAR; PG8_WAIT_L(0); PG8_MMA(1, 0, At, B0); PG8_BAR; PG8_SCHED;
;             PG8_STAGE(PG8_SB(1, 1), b3 + hstep, voffB);
;             PG8_WAIT_V(6); PG8_BAR; PG8_MMA(1, 1, At, B1); PG8_BAR;
;             }
;         }
;         if constexpr (ALIGN_EPI) { if (wr == 0) PG8_BAR; }
	s_setprio 0
	s_mov_b32 m0, s44
	s_nop 0
	buffer_load_dwordx4 v168, s[16:19], s62 offen lds
	s_mov_b32 m0, s36
	s_nop 0
	buffer_load_dwordx4 v170, s[16:19], s62 offen lds
	v_add_u32_e32 v0, 0x18000, v172
	ds_read_b128 v[130:133], v0
	ds_read_b128 v[134:137], v0 offset:1024
	ds_read_b128 v[138:141], v0 offset:2048
	ds_read_b128 v[142:145], v0 offset:3072
	v_add_u32_e32 v0, 0x1c000, v172
	ds_read_b128 v[146:149], v0
	ds_read_b128 v[150:153], v0 offset:1024
	ds_read_b128 v[154:157], v0 offset:2048
	ds_read_b128 v[158:161], v0 offset:3072
	s_add_i32 s62, s62, 0xc0000
	s_mov_b32 m0, s37
	ds_read_b128 v[162:165], v173 offset:32768
	ds_read_b128 v[174:177], v173 offset:33792
	ds_read_b128 v[178:181], v173 offset:34816
	ds_read_b128 v[182:185], v173 offset:35840
	ds_read_b128 v[186:189], v173 offset:36864
	ds_read_b128 v[190:193], v173 offset:37888
	ds_read_b128 v[194:197], v173 offset:38912
	ds_read_b128 v[200:203], v173 offset:39936
	buffer_load_dwordx4 v168, s[16:19], s62 offen lds
	s_mov_b32 m0, s38
	s_nop 0
	buffer_load_dwordx4 v170, s[16:19], s62 offen lds
	s_waitcnt vmcnt(8)
	s_waitcnt lgkmcnt(0)
	s_setprio 1
	s_barrier
	v_mfma_f32_16x16x32_bf16 v[126:129], v[130:133], v[162:165], v[126:129]
	v_mfma_f32_16x16x32_bf16 v[122:125], v[138:141], v[162:165], v[122:125]
	v_mfma_f32_16x16x32_bf16 v[110:113], v[130:133], v[178:181], v[110:113]
	v_mfma_f32_16x16x32_bf16 v[106:109], v[138:141], v[178:181], v[106:109]
	v_mfma_f32_16x16x32_bf16 v[94:97], v[130:133], v[186:189], v[94:97]
	v_mfma_f32_16x16x32_bf16 v[90:93], v[138:141], v[186:189], v[90:93]
	v_mfma_f32_16x16x32_bf16 v[78:81], v[130:133], v[194:197], v[78:81]
	v_mfma_f32_16x16x32_bf16 v[74:77], v[138:141], v[194:197], v[74:77]
	v_mfma_f32_16x16x32_bf16 v[126:129], v[134:137], v[174:177], v[126:129]
	v_mfma_f32_16x16x32_bf16 v[122:125], v[142:145], v[174:177], v[122:125]
	v_mfma_f32_16x16x32_bf16 v[110:113], v[134:137], v[182:185], v[110:113]
	v_mfma_f32_16x16x32_bf16 v[106:109], v[142:145], v[182:185], v[106:109]
	v_mfma_f32_16x16x32_bf16 v[94:97], v[134:137], v[190:193], v[94:97]
	v_mfma_f32_16x16x32_bf16 v[90:93], v[142:145], v[190:193], v[90:93]
	v_mfma_f32_16x16x32_bf16 v[78:81], v[134:137], v[200:203], v[78:81]
	v_mfma_f32_16x16x32_bf16 v[74:77], v[142:145], v[200:203], v[74:77]
	v_mfma_f32_16x16x32_bf16 v[118:121], v[146:149], v[162:165], v[118:121]
	v_mfma_f32_16x16x32_bf16 v[114:117], v[154:157], v[162:165], v[114:117]
	v_mfma_f32_16x16x32_bf16 v[102:105], v[146:149], v[178:181], v[102:105]
	v_mfma_f32_16x16x32_bf16 v[98:101], v[154:157], v[178:181], v[98:101]
	v_mfma_f32_16x16x32_bf16 v[86:89], v[146:149], v[186:189], v[86:89]
	v_mfma_f32_16x16x32_bf16 v[82:85], v[154:157], v[186:189], v[82:85]
	v_mfma_f32_16x16x32_bf16 v[70:73], v[146:149], v[194:197], v[70:73]
	v_mfma_f32_16x16x32_bf16 v[66:69], v[154:157], v[194:197], v[66:69]
	v_mfma_f32_16x16x32_bf16 v[118:121], v[150:153], v[174:177], v[118:121]
	v_mfma_f32_16x16x32_bf16 v[114:117], v[158:161], v[174:177], v[114:117]
	v_mfma_f32_16x16x32_bf16 v[102:105], v[150:153], v[182:185], v[102:105]
	v_mfma_f32_16x16x32_bf16 v[98:101], v[158:161], v[182:185], v[98:101]
	v_mfma_f32_16x16x32_bf16 v[86:89], v[150:153], v[190:193], v[86:89]
	v_mfma_f32_16x16x32_bf16 v[82:85], v[158:161], v[190:193], v[82:85]
	v_mfma_f32_16x16x32_bf16 v[70:73], v[150:153], v[200:203], v[70:73]
	v_mfma_f32_16x16x32_bf16 v[66:69], v[158:161], v[200:203], v[66:69]
	s_barrier
	s_setprio 0
	s_mov_b32 m0, s39
	s_or_b32 s62, s60, 0x80
	ds_read_b128 v[162:165], v173 offset:49152
	ds_read_b128 v[174:177], v173 offset:50176
	ds_read_b128 v[178:181], v173 offset:51200
	ds_read_b128 v[182:185], v173 offset:52224
	ds_read_b128 v[186:189], v173 offset:53248
	ds_read_b128 v[190:193], v173 offset:54272
	ds_read_b128 v[194:197], v173 offset:55296
	ds_read_b128 v[200:203], v173 offset:56320
	buffer_load_dwordx4 v169, s[12:15], s62 offen lds
	s_mov_b32 m0, s40
	s_add_i32 s60, s60, 0xb0080
	buffer_load_dwordx4 v171, s[12:15], s62 offen lds
	s_mov_b32 m0, s43
	s_nop 0
	buffer_load_dwordx4 v169, s[12:15], s60 offen lds
	s_mov_b32 m0, s42
	s_nop 0
	buffer_load_dwordx4 v171, s[12:15], s60 offen lds
	s_waitcnt vmcnt(6)
	s_waitcnt lgkmcnt(0)
	s_setprio 1
	s_barrier
	v_mfma_f32_16x16x32_bf16 v[62:65], v[130:133], v[162:165], v[62:65]
	v_mfma_f32_16x16x32_bf16 v[58:61], v[138:141], v[162:165], v[58:61]
	v_mfma_f32_16x16x32_bf16 v[46:49], v[130:133], v[178:181], v[46:49]
	v_mfma_f32_16x16x32_bf16 v[42:45], v[138:141], v[178:181], v[42:45]
	v_mfma_f32_16x16x32_bf16 v[30:33], v[130:133], v[186:189], v[30:33]
	v_mfma_f32_16x16x32_bf16 v[26:29], v[138:141], v[186:189], v[26:29]
	v_mfma_f32_16x16x32_bf16 v[14:17], v[130:133], v[194:197], v[14:17]
	v_mfma_f32_16x16x32_bf16 v[10:13], v[138:141], v[194:197], v[10:13]
	v_mfma_f32_16x16x32_bf16 v[62:65], v[134:137], v[174:177], v[62:65]
	v_mfma_f32_16x16x32_bf16 v[58:61], v[142:145], v[174:177], v[58:61]
	v_mfma_f32_16x16x32_bf16 v[46:49], v[134:137], v[182:185], v[46:49]
	v_mfma_f32_16x16x32_bf16 v[42:45], v[142:145], v[182:185], v[42:45]
	v_mfma_f32_16x16x32_bf16 v[30:33], v[134:137], v[190:193], v[30:33]
	v_mfma_f32_16x16x32_bf16 v[26:29], v[142:145], v[190:193], v[26:29]
	v_mfma_f32_16x16x32_bf16 v[14:17], v[134:137], v[200:203], v[14:17]
	v_mfma_f32_16x16x32_bf16 v[10:13], v[142:145], v[200:203], v[10:13]
	v_mfma_f32_16x16x32_bf16 v[54:57], v[146:149], v[162:165], v[54:57]
	v_mfma_f32_16x16x32_bf16 v[50:53], v[154:157], v[162:165], v[50:53]
	v_mfma_f32_16x16x32_bf16 v[38:41], v[146:149], v[178:181], v[38:41]
	v_mfma_f32_16x16x32_bf16 v[34:37], v[154:157], v[178:181], v[34:37]
	v_mfma_f32_16x16x32_bf16 v[22:25], v[146:149], v[186:189], v[22:25]
	v_mfma_f32_16x16x32_bf16 v[18:21], v[154:157], v[186:189], v[18:21]
	v_mfma_f32_16x16x32_bf16 v[6:9], v[146:149], v[194:197], v[6:9]
	v_mfma_f32_16x16x32_bf16 v[2:5], v[154:157], v[194:197], v[2:5]
	v_mfma_f32_16x16x32_bf16 v[54:57], v[150:153], v[174:177], v[54:57]
	v_mfma_f32_16x16x32_bf16 v[50:53], v[158:161], v[174:177], v[50:53]
	v_mfma_f32_16x16x32_bf16 v[38:41], v[150:153], v[182:185], v[38:41]
	v_mfma_f32_16x16x32_bf16 v[34:37], v[158:161], v[182:185], v[34:37]
	v_mfma_f32_16x16x32_bf16 v[22:25], v[150:153], v[190:193], v[22:25]
	v_mfma_f32_16x16x32_bf16 v[18:21], v[158:161], v[190:193], v[18:21]
	v_mfma_f32_16x16x32_bf16 v[6:9], v[150:153], v[200:203], v[6:9]
	v_mfma_f32_16x16x32_bf16 v[2:5], v[158:161], v[200:203], v[2:5]
	s_barrier
	s_setprio 0
	s_add_i32 s59, s59, 2
	s_addk_i32 s2, 0x100
	s_addk_i32 s3, 0x100
	s_cmp_gt_u32 s59, 41
	s_cbranch_scc0 .LBB0_1614
	s_mov_b32 m0, s41
	s_nop 0
	buffer_load_dwordx4 v168, s[16:19], s61 offen lds
	s_mov_b32 m0, s33
	s_nop 0
	buffer_load_dwordx4 v170, s[16:19], s61 offen lds
	v_readlane_b32 s2, v251, 45
	v_readlane_b32 s3, v251, 46
	s_and_b64 vcc, exec, s[2:3]
	s_cbranch_vccz .LBB0_1617
	s_barrier
